# v5 + removed the redundant second accumulator-zeroing block in the four gemm_phase unit heads
# speedup vs baseline: 1.0018x; 1.0014x over previous
; #define PG8_WAIT_V(n) asm volatile("s_waitcnt vmcnt(" #n ")" ::: "memory")
; #define PG8_WAIT_L(n) asm volatile("s_waitcnt lgkmcnt(" #n ")" ::: "memory")
; template <class Epi, class Sched>
; __device__ __forceinline__ void gemm_phase(LAS unsigned char* lds, const Gemm g, const Sched S, const Epi E, const int tid) {
;     ...
;         const bool has_next = S.next(ui + 1, nxt);
;         const char* nA = has_next ? (const char*)g.A + (size_t)nxt.pm * tstepA : cA; const char* nB = has_next ? (const char*)g.Bt + (size_t)nxt.pn * tstepB : cB;
;         for (int t = 0; t < nt; t += 2) {
;             const bool last = (t == nt - 2);
;             const char* a1 = cA + (size_t)(t + 1) * kstep;
;             const char* a2 = last ? nA : cA + (size_t)(t + 2) * kstep; const char* b2 = last ? nB : cB + (size_t)(t + 2) * kstep;
;             const char* a3 = a2 + kstep; const char* b3 = b2 + kstep;
;             PG8_LDB(B0, 0, 0); PG8_LDB(B1, 0, 1); PG8_SCHED; PG8_LDA(At, 0, 0); PG8_STAGE(PG8_SA(1, 1), a1 + hstepA, voffA);
;             PG8_WAIT_V(8); PG8_WAIT_L(0); PG8_BAR; PG8_MMA(0, 0, At, B0); PG8_MMA(0, 1, At, B1); PG8_BAR; PG8_SCHED;
;             PG8_LDA(At, 0, 1); PG8_STAGE(PG8_SB(0, 0), b2, voffB); PG8_STAGE(PG8_SB(0, 1), b2 + hstepB, voffB); PG8_STAGE(PG8_SA(0, 0), a2, voffA);
;             PG8_WAIT_V(8); PG8_WAIT_L(0); PG8_BAR; PG8_MMA(1, 0, At, B0); PG8_MMA(1, 1, At, B1); PG8_BAR; PG8_SCHED;
;             PG8_LDB(B0, 1, 0); PG8_LDB(B1, 1, 1); PG8_SCHED; PG8_LDA(At, 1, 0); PG8_STAGE(PG8_SA(0, 1), a2 + hstepA, voffA);
;             PG8_WAIT_V(8); PG8_WAIT_L(0); PG8_BAR; PG8_MMA(0, 0, At, B0); PG8_MMA(0, 1, At, B1); PG8_BAR; PG8_SCHED;
;             PG8_LDA(At, 1, 1); PG8_STAGE(PG8_SB(1, 0), b3, voffB); PG8_STAGE(PG8_SB(1, 1), b3 + hstepB, voffB); PG8_STAGE(PG8_SA(1, 0), a3, voffA);
;             PG8_WAIT_V(8); PG8_WAIT_L(0); PG8_BAR; PG8_MMA(1, 0, At, B0); PG8_MMA(1, 1, At, B1); PG8_BAR; PG8_SCHED;
;         }
;         if (wr == 0) PG8_BAR;
;         E(acc, cur, wr, wc, fr, fq, rc);
;         if (!has_next) break;
; #pragma unroll
;         for (int a = 0; a < 2; ++a)
; #pragma unroll
;             for (int b = 0; b < 2; ++b)
; #pragma unroll
;                 for (int m = 0; m < 4; ++m)
; #pragma unroll
;                     for (int n = 0; n < 2; ++n) acc[a][b][m][n] = (f32x4){0.f, 0.f, 0.f, 0.f};
;         cur = nxt; cA = nA; cB = nB; ++ui;
.LBB0_91:
	s_ashr_i32 s73, s72, 31
	s_lshl_b64 s[24:25], s[72:73], 19
	s_add_u32 s26, s3, s24
	s_addc_u32 s27, s14, s25
	s_ashr_i32 s71, s70, 31
	s_lshl_b64 s[24:25], s[70:71], 19
	v_readlane_b32 s40, v254, 44
	v_readlane_b32 s41, v254, 45
	s_add_u32 s74, s40, s24
	v_mov_b32_e32 v129, 0
	s_addc_u32 s75, s41, s25
	s_andn2_b64 vcc, exec, s[22:23]
	v_mov_b32_e32 v128, v129
	v_mov_b32_e32 v127, v129
	v_mov_b32_e32 v126, v129
	v_mov_b32_e32 v125, v129
	v_mov_b32_e32 v124, v129
	v_mov_b32_e32 v123, v129
	v_mov_b32_e32 v122, v129
	v_mov_b32_e32 v121, v129
	v_mov_b32_e32 v120, v129
	v_mov_b32_e32 v119, v129
	v_mov_b32_e32 v118, v129
	v_mov_b32_e32 v117, v129
	v_mov_b32_e32 v116, v129
	v_mov_b32_e32 v115, v129
	v_mov_b32_e32 v114, v129
	v_mov_b32_e32 v113, v129
	v_mov_b32_e32 v112, v129
	v_mov_b32_e32 v111, v129
	v_mov_b32_e32 v110, v129
	v_mov_b32_e32 v109, v129
	v_mov_b32_e32 v108, v129
	v_mov_b32_e32 v107, v129
	v_mov_b32_e32 v106, v129
	v_mov_b32_e32 v105, v129
	v_mov_b32_e32 v104, v129
	v_mov_b32_e32 v103, v129
	v_mov_b32_e32 v102, v129
	v_mov_b32_e32 v101, v129
	v_mov_b32_e32 v100, v129
	v_mov_b32_e32 v99, v129
	v_mov_b32_e32 v98, v129
	v_mov_b32_e32 v65, v129
	v_mov_b32_e32 v64, v129
	v_mov_b32_e32 v63, v129
	v_mov_b32_e32 v62, v129
	v_mov_b32_e32 v61, v129
	v_mov_b32_e32 v60, v129
	v_mov_b32_e32 v59, v129
	v_mov_b32_e32 v58, v129
	v_mov_b32_e32 v57, v129
	v_mov_b32_e32 v56, v129
	v_mov_b32_e32 v55, v129
	v_mov_b32_e32 v54, v129
	v_mov_b32_e32 v53, v129
	v_mov_b32_e32 v52, v129
	v_mov_b32_e32 v51, v129
	v_mov_b32_e32 v50, v129
	v_mov_b32_e32 v49, v129
	v_mov_b32_e32 v48, v129
	v_mov_b32_e32 v47, v129
	v_mov_b32_e32 v46, v129
	v_mov_b32_e32 v45, v129
	v_mov_b32_e32 v44, v129
	v_mov_b32_e32 v43, v129
	v_mov_b32_e32 v42, v129
	v_mov_b32_e32 v41, v129
	v_mov_b32_e32 v40, v129
	v_mov_b32_e32 v39, v129
	v_mov_b32_e32 v38, v129
	v_mov_b32_e32 v37, v129
	v_mov_b32_e32 v36, v129
	v_mov_b32_e32 v35, v129
	v_mov_b32_e32 v34, v129
	v_mov_b32_e32 v97, v129
	v_mov_b32_e32 v96, v129
	v_mov_b32_e32 v95, v129
	v_mov_b32_e32 v94, v129
	v_mov_b32_e32 v93, v129
	v_mov_b32_e32 v92, v129
	v_mov_b32_e32 v91, v129
	v_mov_b32_e32 v90, v129
	v_mov_b32_e32 v89, v129
	v_mov_b32_e32 v88, v129
	v_mov_b32_e32 v87, v129
	v_mov_b32_e32 v86, v129
	v_mov_b32_e32 v85, v129
	v_mov_b32_e32 v84, v129
	v_mov_b32_e32 v83, v129
	v_mov_b32_e32 v82, v129
	v_mov_b32_e32 v81, v129
	v_mov_b32_e32 v80, v129
	v_mov_b32_e32 v79, v129
	v_mov_b32_e32 v78, v129
	v_mov_b32_e32 v77, v129
	v_mov_b32_e32 v76, v129
	v_mov_b32_e32 v75, v129
	v_mov_b32_e32 v74, v129
	v_mov_b32_e32 v73, v129
	v_mov_b32_e32 v72, v129
	v_mov_b32_e32 v71, v129
	v_mov_b32_e32 v70, v129
	v_mov_b32_e32 v69, v129
	v_mov_b32_e32 v68, v129
	v_mov_b32_e32 v67, v129
	v_mov_b32_e32 v66, v129
	v_mov_b32_e32 v33, v129
	v_mov_b32_e32 v32, v129
	v_mov_b32_e32 v31, v129
	v_mov_b32_e32 v30, v129
	v_mov_b32_e32 v29, v129
	v_mov_b32_e32 v28, v129
	v_mov_b32_e32 v27, v129
	v_mov_b32_e32 v26, v129
	v_mov_b32_e32 v25, v129
	v_mov_b32_e32 v24, v129
	v_mov_b32_e32 v23, v129
	v_mov_b32_e32 v22, v129
	v_mov_b32_e32 v21, v129
	v_mov_b32_e32 v20, v129
	v_mov_b32_e32 v19, v129
	v_mov_b32_e32 v18, v129
	v_mov_b32_e32 v17, v129
	v_mov_b32_e32 v16, v129
	v_mov_b32_e32 v15, v129
	v_mov_b32_e32 v14, v129
	v_mov_b32_e32 v13, v129
	v_mov_b32_e32 v12, v129
	v_mov_b32_e32 v11, v129
	v_mov_b32_e32 v10, v129
	v_mov_b32_e32 v9, v129
	v_mov_b32_e32 v8, v129
	v_mov_b32_e32 v7, v129
	v_mov_b32_e32 v6, v129
	v_mov_b32_e32 v5, v129
	v_mov_b32_e32 v4, v129
	v_mov_b32_e32 v3, v129
	v_mov_b32_e32 v2, v129
	s_cbranch_vccnz .LBB0_95
	s_and_b64 s[24:25], s[4:5], exec
	s_cselect_b32 s7, s27, s21
	s_cselect_b32 s9, s26, s20
	s_cselect_b32 s35, s75, s11
	s_cselect_b32 s36, s74, s10
	s_add_u32 s37, s10, 0x100
	s_addc_u32 s38, s11, 0
	s_add_u32 s10, s20, 0x40080
	v_mov_b32_e32 v2, 0
	s_addc_u32 s11, s21, 0
	s_mov_b32 s20, 0
.LBB0_93:
	s_add_i32 s39, s20, 2
	s_add_u32 s21, s10, 0xfffc0080
	s_addc_u32 s24, s11, -1
	s_add_i32 s40, 0, 0x10000
	s_cmp_eq_u32 s34, s20
	s_cselect_b32 s25, s7, s24
	s_cselect_b32 s24, s9, s21
	s_cselect_b32 s21, s35, s38
	s_cselect_b32 s20, s36, s37
	s_add_i32 s42, 0, 0x14000
	v_add_u32_e32 v142, s40, v187
	v_add_u32_e32 v158, s42, v187
	ds_read_b128 v[130:133], v142
	ds_read_b128 v[134:137], v142 offset:1024
	ds_read_b128 v[138:141], v142 offset:2048
	ds_read_b128 v[142:145], v142 offset:3072
	ds_read_b128 v[146:149], v158
	ds_read_b128 v[150:153], v158 offset:1024
	ds_read_b128 v[154:157], v158 offset:2048
	ds_read_b128 v[158:161], v158 offset:3072
	v_lshl_add_u64 v[184:185], s[10:11], 0, v[174:175]
	s_add_i32 m0, s13, 0xc000
	ds_read_b128 v[162:165], v204
	ds_read_b128 v[176:179], v204 offset:1024
	ds_read_b128 v[180:183], v204 offset:2048
	ds_read_b128 v[206:209], v204 offset:3072
	ds_read_b128 v[218:221], v204 offset:4096
	ds_read_b128 v[232:235], v204 offset:5120
	ds_read_b128 v[236:239], v204 offset:6144
	ds_read_b128 v[240:243], v204 offset:7168
	global_load_lds_dwordx4 v[184:185], off
	v_lshl_add_u64 v[184:185], s[10:11], 0, v[172:173]
	s_add_i32 m0, s13, 0xe000
	s_nop 0
	global_load_lds_dwordx4 v[184:185], off
	s_waitcnt vmcnt(8)
	s_waitcnt lgkmcnt(0)
	s_barrier
; #define PG8_STAGE(bufoff, gbase, voff) do { _Pragma("unroll") for (int _i = 0; _i < 2; ++_i) \
;         __builtin_amdgcn_global_load_lds((const unsigned*)((const char*)(gbase) + (voff)[_i]), (LAS unsigned*)(lds + (bufoff) + ldsw + _i * 8192), 16, 0, 0); } while (0)
; #define PG8_LDA(dst, b, h) do { _Pragma("unroll") for (int m = 0; m < 4; ++m) _Pragma("unroll") for (int k = 0; k < 2; ++k) dst[m][k] = *(const LAS bf16x8*)(lds + PG8_SA(b, h) + aoff + m * 2048 + k * 1024); } while (0)
; #define PG8_MMA(ai, bj, At, Bt) do { __builtin_amdgcn_s_setprio(1); _Pragma("unroll") for (int m = 0; m < 4; ++m) _Pragma("unroll") for (int n = 0; n < 2; ++n) _Pragma("unroll") for (int k = 0; k < 2; ++k) \
;         acc[ai][bj][m][n] = __builtin_amdgcn_mfma_f32_16x16x32_bf16(Bt[n][k], At[m][k], acc[ai][bj][m][n], 0, 0, 0); __builtin_amdgcn_s_setprio(0); } while (0)
; #define PG8_WAIT_V(n) asm volatile("s_waitcnt vmcnt(" #n ")" ::: "memory")
; #define PG8_WAIT_L(n) asm volatile("s_waitcnt lgkmcnt(" #n ")" ::: "memory")
; #define PG8_BAR __builtin_amdgcn_s_barrier()
; #define PG8_SCHED __builtin_amdgcn_sched_barrier(0)
; #define PG8_STAGE(bufoff, gbase, voff, q64) do { \
;         __builtin_amdgcn_global_load_lds((const unsigned*)((const char*)(gbase) + (voff)), (LAS unsigned*)(lds + (bufoff) + ldsw), 16, 0, 0); \
;         __builtin_amdgcn_global_load_lds((const unsigned*)((const char*)(gbase) + (q64) + (voff)), (LAS unsigned*)(lds + (bufoff) + ldsw + 8192), 16, 0, 0); } while (0)
; #define PG8_LDA(dst, b, h) do { _Pragma("unroll") for (int m = 0; m < 4; ++m) _Pragma("unroll") for (int k = 0; k < 2; ++k) dst[m][k] = *(const LAS bf16x8*)(lds + PG8_SA(b, h) + aoff + m * 2048 + k * 1024); } while (0)
; #define PG8_WAIT_V(n) asm volatile("s_waitcnt vmcnt(" #n ")" ::: "memory")
; #define PG8_BAR __builtin_amdgcn_s_barrier()
; template <class Epi, class Sched>
; __device__ __forceinline__ void gemm_phase(LAS unsigned char* lds, const Gemm g, const Sched S, const Epi E, const int tid) {
;     ...
;             PG8_WAIT_V(8); PG8_WAIT_L(0); PG8_BAR; PG8_MMA(0, 0, At, B0); PG8_MMA(0, 1, At, B1); PG8_BAR; PG8_SCHED;
;             PG8_LDA(At, 0, 1); PG8_STAGE(PG8_SB(0, 0), b2, voffB); PG8_STAGE(PG8_SB(0, 1), b2 + hstepB, voffB); PG8_STAGE(PG8_SA(0, 0), a2, voffA);
;             PG8_WAIT_V(8); PG8_WAIT_L(0); PG8_BAR; PG8_MMA(1, 0, At, B0); PG8_MMA(1, 1, At, B1); PG8_BAR; PG8_SCHED;
	s_setprio 1
	s_waitcnt lgkmcnt(0)
	v_mfma_f32_16x16x32_bf16 v[126:129], v[130:133], v[162:165], v[126:129]
	v_mfma_f32_16x16x32_bf16 v[122:125], v[138:141], v[162:165], v[122:125]
	v_mfma_f32_16x16x32_bf16 v[118:121], v[130:133], v[180:183], v[118:121]
	v_mfma_f32_16x16x32_bf16 v[114:117], v[138:141], v[180:183], v[114:117]
	v_mfma_f32_16x16x32_bf16 v[110:113], v[130:133], v[218:221], v[110:113]
	v_mfma_f32_16x16x32_bf16 v[106:109], v[138:141], v[218:221], v[106:109]
	v_mfma_f32_16x16x32_bf16 v[102:105], v[130:133], v[236:239], v[102:105]
	v_mfma_f32_16x16x32_bf16 v[98:101], v[138:141], v[236:239], v[98:101]
	v_mfma_f32_16x16x32_bf16 v[126:129], v[134:137], v[176:179], v[126:129]
	v_mfma_f32_16x16x32_bf16 v[122:125], v[142:145], v[176:179], v[122:125]
	v_mfma_f32_16x16x32_bf16 v[118:121], v[134:137], v[206:209], v[118:121]
	v_mfma_f32_16x16x32_bf16 v[114:117], v[142:145], v[206:209], v[114:117]
	v_mfma_f32_16x16x32_bf16 v[110:113], v[134:137], v[232:235], v[110:113]
	v_mfma_f32_16x16x32_bf16 v[106:109], v[142:145], v[232:235], v[106:109]
	v_mfma_f32_16x16x32_bf16 v[102:105], v[134:137], v[240:243], v[102:105]
	v_mfma_f32_16x16x32_bf16 v[98:101], v[142:145], v[240:243], v[98:101]
	s_setprio 0
	s_setprio 1
	v_mfma_f32_16x16x32_bf16 v[62:65], v[146:149], v[162:165], v[62:65]
	v_mfma_f32_16x16x32_bf16 v[58:61], v[154:157], v[162:165], v[58:61]
	v_mfma_f32_16x16x32_bf16 v[54:57], v[146:149], v[180:183], v[54:57]
	v_mfma_f32_16x16x32_bf16 v[50:53], v[154:157], v[180:183], v[50:53]
	v_mfma_f32_16x16x32_bf16 v[46:49], v[146:149], v[218:221], v[46:49]
	v_mfma_f32_16x16x32_bf16 v[42:45], v[154:157], v[218:221], v[42:45]
	v_mfma_f32_16x16x32_bf16 v[38:41], v[146:149], v[236:239], v[38:41]
	v_mfma_f32_16x16x32_bf16 v[34:37], v[154:157], v[236:239], v[34:37]
	v_mfma_f32_16x16x32_bf16 v[62:65], v[150:153], v[176:179], v[62:65]
	v_mfma_f32_16x16x32_bf16 v[58:61], v[158:161], v[176:179], v[58:61]
	v_mfma_f32_16x16x32_bf16 v[54:57], v[150:153], v[206:209], v[54:57]
	v_mfma_f32_16x16x32_bf16 v[50:53], v[158:161], v[206:209], v[50:53]
	v_mfma_f32_16x16x32_bf16 v[46:49], v[150:153], v[232:235], v[46:49]
	v_mfma_f32_16x16x32_bf16 v[42:45], v[158:161], v[232:235], v[42:45]
	v_mfma_f32_16x16x32_bf16 v[38:41], v[150:153], v[240:243], v[38:41]
	v_mfma_f32_16x16x32_bf16 v[34:37], v[158:161], v[240:243], v[34:37]
	s_setprio 0
	s_barrier
	s_add_i32 s40, s40, s12
	v_lshl_add_u64 v[184:185], s[20:21], 0, v[0:1]
	s_mov_b32 m0, s40
	ds_read_b128 v[162:165], v204 offset:16384
	ds_read_b128 v[176:179], v204 offset:17408
	ds_read_b128 v[180:183], v204 offset:18432
	ds_read_b128 v[206:209], v204 offset:19456
	ds_read_b128 v[218:221], v204 offset:20480
	ds_read_b128 v[232:235], v204 offset:21504
	ds_read_b128 v[236:239], v204 offset:22528
	ds_read_b128 v[240:243], v204 offset:23552
	global_load_lds_dwordx4 v[184:185], off
	s_add_i32 m0, s40, 0x2000
	s_add_u32 s40, s20, 0x40000
	v_lshl_add_u64 v[190:191], s[20:21], 0, v[170:171]
	s_addc_u32 s41, s21, 0
	s_add_i32 s42, s42, s12
	global_load_lds_dwordx4 v[190:191], off
	v_lshl_add_u64 v[192:193], s[40:41], 0, v[0:1]
	s_mov_b32 m0, s42
	v_lshl_add_u64 v[194:195], s[24:25], 0, v[168:169]
	global_load_lds_dwordx4 v[192:193], off
	v_lshl_add_u64 v[192:193], s[40:41], 0, v[170:171]
	s_add_i32 m0, s42, 0x2000
	s_nop 0
	global_load_lds_dwordx4 v[192:193], off
	v_lshl_add_u64 v[192:193], s[24:25], 0, v[166:167]
	s_mov_b32 m0, s13
	s_nop 0
	global_load_lds_dwordx4 v[192:193], off
	s_mov_b32 m0, s15
	s_nop 0
	global_load_lds_dwordx4 v[194:195], off
	s_waitcnt vmcnt(8)
	s_waitcnt lgkmcnt(0)
	s_barrier
	s_setprio 1
	s_waitcnt lgkmcnt(0)
	v_mfma_f32_16x16x32_bf16 v[94:97], v[130:133], v[162:165], v[94:97]
	v_mfma_f32_16x16x32_bf16 v[90:93], v[138:141], v[162:165], v[90:93]
	v_mfma_f32_16x16x32_bf16 v[86:89], v[130:133], v[180:183], v[86:89]
	v_mfma_f32_16x16x32_bf16 v[82:85], v[138:141], v[180:183], v[82:85]
	v_mfma_f32_16x16x32_bf16 v[78:81], v[130:133], v[218:221], v[78:81]
	v_mfma_f32_16x16x32_bf16 v[74:77], v[138:141], v[218:221], v[74:77]
	v_mfma_f32_16x16x32_bf16 v[70:73], v[130:133], v[236:239], v[70:73]
	v_mfma_f32_16x16x32_bf16 v[66:69], v[138:141], v[236:239], v[66:69]
	v_mfma_f32_16x16x32_bf16 v[94:97], v[134:137], v[176:179], v[94:97]
	v_mfma_f32_16x16x32_bf16 v[90:93], v[142:145], v[176:179], v[90:93]
	v_mfma_f32_16x16x32_bf16 v[86:89], v[134:137], v[206:209], v[86:89]
	v_mfma_f32_16x16x32_bf16 v[82:85], v[142:145], v[206:209], v[82:85]
	v_mfma_f32_16x16x32_bf16 v[78:81], v[134:137], v[232:235], v[78:81]
	v_mfma_f32_16x16x32_bf16 v[74:77], v[142:145], v[232:235], v[74:77]
	v_mfma_f32_16x16x32_bf16 v[70:73], v[134:137], v[240:243], v[70:73]
	v_mfma_f32_16x16x32_bf16 v[66:69], v[142:145], v[240:243], v[66:69]
	s_setprio 0
	s_setprio 1
	v_mfma_f32_16x16x32_bf16 v[30:33], v[146:149], v[162:165], v[30:33]
	v_mfma_f32_16x16x32_bf16 v[26:29], v[154:157], v[162:165], v[26:29]
	v_mfma_f32_16x16x32_bf16 v[22:25], v[146:149], v[180:183], v[22:25]
	v_mfma_f32_16x16x32_bf16 v[18:21], v[154:157], v[180:183], v[18:21]
	v_mfma_f32_16x16x32_bf16 v[14:17], v[146:149], v[218:221], v[14:17]
	v_mfma_f32_16x16x32_bf16 v[10:13], v[154:157], v[218:221], v[10:13]
	v_mfma_f32_16x16x32_bf16 v[6:9], v[146:149], v[236:239], v[6:9]
	v_mfma_f32_16x16x32_bf16 v[2:5], v[154:157], v[236:239], v[2:5]
	v_mfma_f32_16x16x32_bf16 v[30:33], v[150:153], v[176:179], v[30:33]
	v_mfma_f32_16x16x32_bf16 v[26:29], v[158:161], v[176:179], v[26:29]
	v_mfma_f32_16x16x32_bf16 v[22:25], v[150:153], v[206:209], v[22:25]
	v_mfma_f32_16x16x32_bf16 v[18:21], v[158:161], v[206:209], v[18:21]
	v_mfma_f32_16x16x32_bf16 v[14:17], v[150:153], v[232:235], v[14:17]
	v_mfma_f32_16x16x32_bf16 v[10:13], v[158:161], v[232:235], v[10:13]
	v_mfma_f32_16x16x32_bf16 v[6:9], v[150:153], v[240:243], v[6:9]
	v_mfma_f32_16x16x32_bf16 v[2:5], v[158:161], v[240:243], v[2:5]
	s_setprio 0
	s_barrier
; #define PG8_STAGE(bufoff, gbase, voff) do { _Pragma("unroll") for (int _i = 0; _i < 2; ++_i) \
;         __builtin_amdgcn_global_load_lds((const unsigned*)((const char*)(gbase) + (voff)[_i]), (LAS unsigned*)(lds + (bufoff) + ldsw + _i * 8192), 16, 0, 0); } while (0)
; #define PG8_LDA(dst, b, h) do { _Pragma("unroll") for (int m = 0; m < 4; ++m) _Pragma("unroll") for (int k = 0; k < 2; ++k) dst[m][k] = *(const LAS bf16x8*)(lds + PG8_SA(b, h) + aoff + m * 2048 + k * 1024); } while (0)
; #define PG8_LDB(dst, b, h) do { _Pragma("unroll") for (int n = 0; n < 2; ++n) _Pragma("unroll") for (int k = 0; k < 2; ++k) dst[n][k] = *(const LAS bf16x8*)(lds + PG8_SB(b, h) + boff + n * 2048 + k * 1024); } while (0)
; #define PG8_MMA(ai, bj, At, Bt) do { __builtin_amdgcn_s_setprio(1); _Pragma("unroll") for (int m = 0; m < 4; ++m) _Pragma("unroll") for (int n = 0; n < 2; ++n) _Pragma("unroll") for (int k = 0; k < 2; ++k) \
;         acc[ai][bj][m][n] = __builtin_amdgcn_mfma_f32_16x16x32_bf16(Bt[n][k], At[m][k], acc[ai][bj][m][n], 0, 0, 0); __builtin_amdgcn_s_setprio(0); } while (0)
; #define PG8_WAIT_V(n) asm volatile("s_waitcnt vmcnt(" #n ")" ::: "memory")
; #define PG8_WAIT_L(n) asm volatile("s_waitcnt lgkmcnt(" #n ")" ::: "memory")
; #define PG8_BAR __builtin_amdgcn_s_barrier()
; #define PG8_SCHED __builtin_amdgcn_sched_barrier(0)
; #define PG8_STAGE(bufoff, gbase, voff, q64) do { \
;         __builtin_amdgcn_global_load_lds((const unsigned*)((const char*)(gbase) + (voff)), (LAS unsigned*)(lds + (bufoff) + ldsw), 16, 0, 0); \
;         __builtin_amdgcn_global_load_lds((const unsigned*)((const char*)(gbase) + (q64) + (voff)), (LAS unsigned*)(lds + (bufoff) + ldsw + 8192), 16, 0, 0); } while (0)
; #define PG8_LDA(dst, b, h) do { _Pragma("unroll") for (int m = 0; m < 4; ++m) _Pragma("unroll") for (int k = 0; k < 2; ++k) dst[m][k] = *(const LAS bf16x8*)(lds + PG8_SA(b, h) + aoff + m * 2048 + k * 1024); } while (0)
; #define PG8_BAR __builtin_amdgcn_s_barrier()
; template <class Epi, class Sched>
; __device__ __forceinline__ void gemm_phase(LAS unsigned char* lds, const Gemm g, const Sched S, const Epi E, const int tid) {
;     ...
;             PG8_LDB(B0, 1, 0); PG8_LDB(B1, 1, 1); PG8_SCHED; PG8_LDA(At, 1, 0); PG8_STAGE(PG8_SA(0, 1), a2 + hstepA, voffA);
;             PG8_WAIT_V(8); PG8_WAIT_L(0); PG8_BAR; PG8_MMA(0, 0, At, B0); PG8_MMA(0, 1, At, B1); PG8_BAR; PG8_SCHED;
	s_add_i32 s40, 0, 0x18000
	s_add_i32 s41, 0, 0x1c000
	v_add_u32_e32 v142, s40, v187
	v_add_u32_e32 v158, s41, v187
	ds_read_b128 v[130:133], v142
	ds_read_b128 v[134:137], v142 offset:1024
	ds_read_b128 v[138:141], v142 offset:2048
	ds_read_b128 v[142:145], v142 offset:3072
	ds_read_b128 v[146:149], v158
	ds_read_b128 v[150:153], v158 offset:1024
	ds_read_b128 v[154:157], v158 offset:2048
	ds_read_b128 v[158:161], v158 offset:3072
	s_add_u32 s24, s24, 0x40000
	s_addc_u32 s25, s25, 0
	s_mov_b32 m0, s18
	v_lshl_add_u64 v[210:211], s[24:25], 0, v[166:167]
	ds_read_b128 v[162:165], v204 offset:32768
	ds_read_b128 v[176:179], v204 offset:33792
	ds_read_b128 v[180:183], v204 offset:34816
	ds_read_b128 v[206:209], v204 offset:35840
	ds_read_b128 v[218:221], v204 offset:36864
	ds_read_b128 v[232:235], v204 offset:37888
	ds_read_b128 v[236:239], v204 offset:38912
	ds_read_b128 v[240:243], v204 offset:39936
	global_load_lds_dwordx4 v[210:211], off
	v_lshl_add_u64 v[210:211], s[24:25], 0, v[168:169]
	s_mov_b32 m0, s19
	s_nop 0
	global_load_lds_dwordx4 v[210:211], off
	s_waitcnt vmcnt(8)
	s_waitcnt lgkmcnt(0)
	s_barrier
	s_setprio 1
	s_waitcnt lgkmcnt(0)
	v_mfma_f32_16x16x32_bf16 v[126:129], v[130:133], v[162:165], v[126:129]
	v_mfma_f32_16x16x32_bf16 v[122:125], v[138:141], v[162:165], v[122:125]
	v_mfma_f32_16x16x32_bf16 v[118:121], v[130:133], v[180:183], v[118:121]
	v_mfma_f32_16x16x32_bf16 v[114:117], v[138:141], v[180:183], v[114:117]
	v_mfma_f32_16x16x32_bf16 v[110:113], v[130:133], v[218:221], v[110:113]
	v_mfma_f32_16x16x32_bf16 v[106:109], v[138:141], v[218:221], v[106:109]
	v_mfma_f32_16x16x32_bf16 v[102:105], v[130:133], v[236:239], v[102:105]
	v_mfma_f32_16x16x32_bf16 v[98:101], v[138:141], v[236:239], v[98:101]
	v_mfma_f32_16x16x32_bf16 v[126:129], v[134:137], v[176:179], v[126:129]
	v_mfma_f32_16x16x32_bf16 v[122:125], v[142:145], v[176:179], v[122:125]
	v_mfma_f32_16x16x32_bf16 v[118:121], v[134:137], v[206:209], v[118:121]
	v_mfma_f32_16x16x32_bf16 v[114:117], v[142:145], v[206:209], v[114:117]
	v_mfma_f32_16x16x32_bf16 v[110:113], v[134:137], v[232:235], v[110:113]
	v_mfma_f32_16x16x32_bf16 v[106:109], v[142:145], v[232:235], v[106:109]
	v_mfma_f32_16x16x32_bf16 v[102:105], v[134:137], v[240:243], v[102:105]
	v_mfma_f32_16x16x32_bf16 v[98:101], v[142:145], v[240:243], v[98:101]
	s_setprio 0
	s_setprio 1
	v_mfma_f32_16x16x32_bf16 v[62:65], v[146:149], v[162:165], v[62:65]
	v_mfma_f32_16x16x32_bf16 v[58:61], v[154:157], v[162:165], v[58:61]
	v_mfma_f32_16x16x32_bf16 v[54:57], v[146:149], v[180:183], v[54:57]
	v_mfma_f32_16x16x32_bf16 v[50:53], v[154:157], v[180:183], v[50:53]
	v_mfma_f32_16x16x32_bf16 v[46:49], v[146:149], v[218:221], v[46:49]
	v_mfma_f32_16x16x32_bf16 v[42:45], v[154:157], v[218:221], v[42:45]
	v_mfma_f32_16x16x32_bf16 v[38:41], v[146:149], v[236:239], v[38:41]
	v_mfma_f32_16x16x32_bf16 v[34:37], v[154:157], v[236:239], v[34:37]
	v_mfma_f32_16x16x32_bf16 v[62:65], v[150:153], v[176:179], v[62:65]
	v_mfma_f32_16x16x32_bf16 v[58:61], v[158:161], v[176:179], v[58:61]
	v_mfma_f32_16x16x32_bf16 v[54:57], v[150:153], v[206:209], v[54:57]
	v_mfma_f32_16x16x32_bf16 v[50:53], v[158:161], v[206:209], v[50:53]
	v_mfma_f32_16x16x32_bf16 v[46:49], v[150:153], v[232:235], v[46:49]
	v_mfma_f32_16x16x32_bf16 v[42:45], v[158:161], v[232:235], v[42:45]
	v_mfma_f32_16x16x32_bf16 v[38:41], v[150:153], v[240:243], v[38:41]
	v_mfma_f32_16x16x32_bf16 v[34:37], v[158:161], v[240:243], v[34:37]
	s_setprio 0
	s_barrier
; #define PG8_STAGE(bufoff, gbase, voff) do { _Pragma("unroll") for (int _i = 0; _i < 2; ++_i) \
;         __builtin_amdgcn_global_load_lds((const unsigned*)((const char*)(gbase) + (voff)[_i]), (LAS unsigned*)(lds + (bufoff) + ldsw + _i * 8192), 16, 0, 0); } while (0)
; #define PG8_LDA(dst, b, h) do { _Pragma("unroll") for (int m = 0; m < 4; ++m) _Pragma("unroll") for (int k = 0; k < 2; ++k) dst[m][k] = *(const LAS bf16x8*)(lds + PG8_SA(b, h) + aoff + m * 2048 + k * 1024); } while (0)
; #define PG8_MMA(ai, bj, At, Bt) do { __builtin_amdgcn_s_setprio(1); _Pragma("unroll") for (int m = 0; m < 4; ++m) _Pragma("unroll") for (int n = 0; n < 2; ++n) _Pragma("unroll") for (int k = 0; k < 2; ++k) \
;         acc[ai][bj][m][n] = __builtin_amdgcn_mfma_f32_16x16x32_bf16(Bt[n][k], At[m][k], acc[ai][bj][m][n], 0, 0, 0); __builtin_amdgcn_s_setprio(0); } while (0)
; #define PG8_WAIT_V(n) asm volatile("s_waitcnt vmcnt(" #n ")" ::: "memory")
; #define PG8_WAIT_L(n) asm volatile("s_waitcnt lgkmcnt(" #n ")" ::: "memory")
; #define PG8_BAR __builtin_amdgcn_s_barrier()
; #define PG8_SCHED __builtin_amdgcn_sched_barrier(0)
; #define PG8_STAGE(bufoff, gbase, voff, q64) do { \
;         __builtin_amdgcn_global_load_lds((const unsigned*)((const char*)(gbase) + (voff)), (LAS unsigned*)(lds + (bufoff) + ldsw), 16, 0, 0); \
;         __builtin_amdgcn_global_load_lds((const unsigned*)((const char*)(gbase) + (q64) + (voff)), (LAS unsigned*)(lds + (bufoff) + ldsw + 8192), 16, 0, 0); } while (0)
; #define PG8_LDA(dst, b, h) do { _Pragma("unroll") for (int m = 0; m < 4; ++m) _Pragma("unroll") for (int k = 0; k < 2; ++k) dst[m][k] = *(const LAS bf16x8*)(lds + PG8_SA(b, h) + aoff + m * 2048 + k * 1024); } while (0)
; #define PG8_WAIT_V(n) asm volatile("s_waitcnt vmcnt(" #n ")" ::: "memory")
; #define PG8_WAIT_L(n) asm volatile("s_waitcnt lgkmcnt(" #n ")" ::: "memory")
; #define PG8_BAR __builtin_amdgcn_s_barrier()
; template <class Epi, class Sched>
; __device__ __forceinline__ void gemm_phase(LAS unsigned char* lds, const Gemm g, const Sched S, const Epi E, const int tid) {
;     ...
;             PG8_LDA(At, 1, 1); PG8_STAGE(PG8_SB(1, 0), b3, voffB); PG8_STAGE(PG8_SB(1, 1), b3 + hstepB, voffB); PG8_STAGE(PG8_SA(1, 0), a3, voffA);
;             PG8_WAIT_V(8); PG8_WAIT_L(0); PG8_BAR; PG8_MMA(1, 0, At, B0); PG8_MMA(1, 1, At, B1); PG8_BAR; PG8_SCHED;
;         }
	s_add_i32 s24, s40, s12
	v_lshl_add_u64 v[184:185], v[184:185], 0, s[0:1]
	s_mov_b32 m0, s24
	ds_read_b128 v[162:165], v204 offset:49152
	ds_read_b128 v[176:179], v204 offset:50176
	ds_read_b128 v[180:183], v204 offset:51200
	ds_read_b128 v[206:209], v204 offset:52224
	ds_read_b128 v[218:221], v204 offset:53248
	ds_read_b128 v[232:235], v204 offset:54272
	ds_read_b128 v[236:239], v204 offset:55296
	ds_read_b128 v[240:243], v204 offset:56320
	global_load_lds_dwordx4 v[184:185], off
	s_add_i32 m0, s24, 0x2000
	s_add_u32 s20, s20, 0x40080
	v_lshl_add_u64 v[184:185], v[190:191], 0, s[0:1]
	s_addc_u32 s21, s21, 0
	s_add_i32 s24, s41, s12
	global_load_lds_dwordx4 v[184:185], off
	v_lshl_add_u64 v[184:185], s[20:21], 0, v[0:1]
	s_mov_b32 m0, s24
	s_nop 0
	global_load_lds_dwordx4 v[184:185], off
	v_lshl_add_u64 v[184:185], s[20:21], 0, v[170:171]
	s_add_i32 m0, s24, 0x2000
	s_nop 0
	global_load_lds_dwordx4 v[184:185], off
	v_lshl_add_u64 v[184:185], v[192:193], 0, s[0:1]
	s_mov_b32 m0, s29
	s_nop 0
	global_load_lds_dwordx4 v[184:185], off
	v_lshl_add_u64 v[184:185], v[194:195], 0, s[0:1]
	s_mov_b32 m0, s31
	s_nop 0
	global_load_lds_dwordx4 v[184:185], off
	s_waitcnt vmcnt(8)
	s_waitcnt lgkmcnt(0)
	s_barrier
	s_setprio 1
	s_waitcnt lgkmcnt(0)
	v_mfma_f32_16x16x32_bf16 v[94:97], v[130:133], v[162:165], v[94:97]
	v_mfma_f32_16x16x32_bf16 v[90:93], v[138:141], v[162:165], v[90:93]
	v_mfma_f32_16x16x32_bf16 v[86:89], v[130:133], v[180:183], v[86:89]
	v_mfma_f32_16x16x32_bf16 v[82:85], v[138:141], v[180:183], v[82:85]
	v_mfma_f32_16x16x32_bf16 v[78:81], v[130:133], v[218:221], v[78:81]
	v_mfma_f32_16x16x32_bf16 v[74:77], v[138:141], v[218:221], v[74:77]
	v_mfma_f32_16x16x32_bf16 v[70:73], v[130:133], v[236:239], v[70:73]
	v_mfma_f32_16x16x32_bf16 v[66:69], v[138:141], v[236:239], v[66:69]
	v_mfma_f32_16x16x32_bf16 v[94:97], v[134:137], v[176:179], v[94:97]
	v_mfma_f32_16x16x32_bf16 v[90:93], v[142:145], v[176:179], v[90:93]
	v_mfma_f32_16x16x32_bf16 v[86:89], v[134:137], v[206:209], v[86:89]
	v_mfma_f32_16x16x32_bf16 v[82:85], v[142:145], v[206:209], v[82:85]
	v_mfma_f32_16x16x32_bf16 v[78:81], v[134:137], v[232:235], v[78:81]
	v_mfma_f32_16x16x32_bf16 v[74:77], v[142:145], v[232:235], v[74:77]
	v_mfma_f32_16x16x32_bf16 v[70:73], v[134:137], v[240:243], v[70:73]
	v_mfma_f32_16x16x32_bf16 v[66:69], v[142:145], v[240:243], v[66:69]
	s_setprio 0
	s_setprio 1
	v_mfma_f32_16x16x32_bf16 v[30:33], v[146:149], v[162:165], v[30:33]
	v_mfma_f32_16x16x32_bf16 v[26:29], v[154:157], v[162:165], v[26:29]
	v_mfma_f32_16x16x32_bf16 v[22:25], v[146:149], v[180:183], v[22:25]
	v_mfma_f32_16x16x32_bf16 v[18:21], v[154:157], v[180:183], v[18:21]
	v_mfma_f32_16x16x32_bf16 v[14:17], v[146:149], v[218:221], v[14:17]
	v_mfma_f32_16x16x32_bf16 v[10:13], v[154:157], v[218:221], v[10:13]
	v_mfma_f32_16x16x32_bf16 v[6:9], v[146:149], v[236:239], v[6:9]
	v_mfma_f32_16x16x32_bf16 v[2:5], v[154:157], v[236:239], v[2:5]
	v_mfma_f32_16x16x32_bf16 v[30:33], v[150:153], v[176:179], v[30:33]
	v_mfma_f32_16x16x32_bf16 v[26:29], v[158:161], v[176:179], v[26:29]
	v_mfma_f32_16x16x32_bf16 v[22:25], v[150:153], v[206:209], v[22:25]
	v_mfma_f32_16x16x32_bf16 v[18:21], v[158:161], v[206:209], v[18:21]
	v_mfma_f32_16x16x32_bf16 v[14:17], v[150:153], v[232:235], v[14:17]
	v_mfma_f32_16x16x32_bf16 v[10:13], v[158:161], v[232:235], v[10:13]
	v_mfma_f32_16x16x32_bf16 v[6:9], v[150:153], v[240:243], v[6:9]
	v_mfma_f32_16x16x32_bf16 v[2:5], v[158:161], v[240:243], v[2:5]
	s_setprio 0
	s_barrier
	s_add_u32 s37, s37, 0x100
	s_addc_u32 s38, s38, 0
	s_add_u32 s10, s10, 0x100
	s_addc_u32 s11, s11, 0
	s_cmp_ge_i32 s39, s28
	s_mov_b32 s20, s39
	s_cbranch_scc0 .LBB0_93
	v_readlane_b32 s36, v254, 54
	v_readlane_b32 s37, v254, 55
	v_readlane_b32 s38, v254, 56
	v_readlane_b32 s39, v254, 57

; #define PG8_WAIT_V(n) asm volatile("s_waitcnt vmcnt(" #n ")" ::: "memory")
; #define PG8_WAIT_L(n) asm volatile("s_waitcnt lgkmcnt(" #n ")" ::: "memory")
; template <class Epi, class Sched>
; __device__ __forceinline__ void gemm_phase(LAS unsigned char* lds, const Gemm g, const Sched S, const Epi E, const int tid) {
;     ...
;         const bool has_next = S.next(ui + 1, nxt);
;         const char* nA = has_next ? (const char*)g.A + (size_t)nxt.pm * tstepA : cA; const char* nB = has_next ? (const char*)g.Bt + (size_t)nxt.pn * tstepB : cB;
;         for (int t = 0; t < nt; t += 2) {
;             const bool last = (t == nt - 2);
;             const char* a1 = cA + (size_t)(t + 1) * kstep;
;             const char* a2 = last ? nA : cA + (size_t)(t + 2) * kstep; const char* b2 = last ? nB : cB + (size_t)(t + 2) * kstep;
;             const char* a3 = a2 + kstep; const char* b3 = b2 + kstep;
;             PG8_LDB(B0, 0, 0); PG8_LDB(B1, 0, 1); PG8_SCHED; PG8_LDA(At, 0, 0); PG8_STAGE(PG8_SA(1, 1), a1 + hstepA, voffA);
;             PG8_WAIT_V(8); PG8_WAIT_L(0); PG8_BAR; PG8_MMA(0, 0, At, B0); PG8_MMA(0, 1, At, B1); PG8_BAR; PG8_SCHED;
;             PG8_LDA(At, 0, 1); PG8_STAGE(PG8_SB(0, 0), b2, voffB); PG8_STAGE(PG8_SB(0, 1), b2 + hstepB, voffB); PG8_STAGE(PG8_SA(0, 0), a2, voffA);
;             PG8_WAIT_V(8); PG8_WAIT_L(0); PG8_BAR; PG8_MMA(1, 0, At, B0); PG8_MMA(1, 1, At, B1); PG8_BAR; PG8_SCHED;
;             PG8_LDB(B0, 1, 0); PG8_LDB(B1, 1, 1); PG8_SCHED; PG8_LDA(At, 1, 0); PG8_STAGE(PG8_SA(0, 1), a2 + hstepA, voffA);
;             PG8_WAIT_V(8); PG8_WAIT_L(0); PG8_BAR; PG8_MMA(0, 0, At, B0); PG8_MMA(0, 1, At, B1); PG8_BAR; PG8_SCHED;
;             PG8_LDA(At, 1, 1); PG8_STAGE(PG8_SB(1, 0), b3, voffB); PG8_STAGE(PG8_SB(1, 1), b3 + hstepB, voffB); PG8_STAGE(PG8_SA(1, 0), a3, voffA);
;             PG8_WAIT_V(8); PG8_WAIT_L(0); PG8_BAR; PG8_MMA(1, 0, At, B0); PG8_MMA(1, 1, At, B1); PG8_BAR; PG8_SCHED;
;         }
;         if (wr == 0) PG8_BAR;
;         E(acc, cur, wr, wc, fr, fq, rc);
;         if (!has_next) break;
; #pragma unroll
;         for (int a = 0; a < 2; ++a)
; #pragma unroll
;             for (int b = 0; b < 2; ++b)
; #pragma unroll
;                 for (int m = 0; m < 4; ++m)
; #pragma unroll
;                     for (int n = 0; n < 2; ++n) acc[a][b][m][n] = (f32x4){0.f, 0.f, 0.f, 0.f};
;         cur = nxt; cA = nA; cB = nB; ++ui;
.LBB0_141:
	s_ashr_i32 s23, s22, 31
	s_lshl_b64 s[26:27], s[22:23], 19
	v_readlane_b32 s28, v254, 44
	v_readlane_b32 s29, v254, 45
	s_add_u32 s26, s28, s26
	s_addc_u32 s27, s29, s27
	s_ashr_i32 s21, s20, 31
	s_lshl_b64 s[28:29], s[20:21], 19
	s_add_u32 s42, s13, s28
	v_mov_b32_e32 v129, 0
	s_addc_u32 s43, s14, s29
	s_andn2_b64 vcc, exec, s[10:11]
	v_mov_b32_e32 v128, v129
	v_mov_b32_e32 v127, v129
	v_mov_b32_e32 v126, v129
	v_mov_b32_e32 v125, v129
	v_mov_b32_e32 v124, v129
	v_mov_b32_e32 v123, v129
	v_mov_b32_e32 v122, v129
	v_mov_b32_e32 v113, v129
	v_mov_b32_e32 v112, v129
	v_mov_b32_e32 v111, v129
	v_mov_b32_e32 v110, v129
	v_mov_b32_e32 v109, v129
	v_mov_b32_e32 v108, v129
	v_mov_b32_e32 v107, v129
	v_mov_b32_e32 v106, v129
	v_mov_b32_e32 v97, v129
	v_mov_b32_e32 v96, v129
	v_mov_b32_e32 v95, v129
	v_mov_b32_e32 v94, v129
	v_mov_b32_e32 v93, v129
	v_mov_b32_e32 v92, v129
	v_mov_b32_e32 v91, v129
	v_mov_b32_e32 v90, v129
	v_mov_b32_e32 v81, v129
	v_mov_b32_e32 v80, v129
	v_mov_b32_e32 v79, v129
	v_mov_b32_e32 v78, v129
	v_mov_b32_e32 v77, v129
	v_mov_b32_e32 v76, v129
	v_mov_b32_e32 v75, v129
	v_mov_b32_e32 v74, v129
	v_mov_b32_e32 v121, v129
	v_mov_b32_e32 v120, v129
	v_mov_b32_e32 v119, v129
	v_mov_b32_e32 v118, v129
	v_mov_b32_e32 v117, v129
	v_mov_b32_e32 v116, v129
	v_mov_b32_e32 v115, v129
	v_mov_b32_e32 v114, v129
	v_mov_b32_e32 v105, v129
	v_mov_b32_e32 v104, v129
	v_mov_b32_e32 v103, v129
	v_mov_b32_e32 v102, v129
	v_mov_b32_e32 v101, v129
	v_mov_b32_e32 v100, v129
	v_mov_b32_e32 v99, v129
	v_mov_b32_e32 v98, v129
	v_mov_b32_e32 v89, v129
	v_mov_b32_e32 v88, v129
	v_mov_b32_e32 v87, v129
	v_mov_b32_e32 v86, v129
	v_mov_b32_e32 v85, v129
	v_mov_b32_e32 v84, v129
	v_mov_b32_e32 v83, v129
	v_mov_b32_e32 v82, v129
	v_mov_b32_e32 v73, v129
	v_mov_b32_e32 v72, v129
	v_mov_b32_e32 v71, v129
	v_mov_b32_e32 v70, v129
	v_mov_b32_e32 v69, v129
	v_mov_b32_e32 v68, v129
	v_mov_b32_e32 v67, v129
	v_mov_b32_e32 v66, v129
	v_mov_b32_e32 v65, v129
	v_mov_b32_e32 v64, v129
	v_mov_b32_e32 v63, v129
	v_mov_b32_e32 v62, v129
	v_mov_b32_e32 v61, v129
	v_mov_b32_e32 v60, v129
	v_mov_b32_e32 v59, v129
	v_mov_b32_e32 v58, v129
	v_mov_b32_e32 v49, v129
	v_mov_b32_e32 v48, v129
	v_mov_b32_e32 v47, v129
	v_mov_b32_e32 v46, v129
	v_mov_b32_e32 v45, v129
	v_mov_b32_e32 v44, v129
	v_mov_b32_e32 v43, v129
	v_mov_b32_e32 v42, v129
	v_mov_b32_e32 v33, v129
	v_mov_b32_e32 v32, v129
	v_mov_b32_e32 v31, v129
	v_mov_b32_e32 v30, v129
	v_mov_b32_e32 v29, v129
	v_mov_b32_e32 v28, v129
	v_mov_b32_e32 v27, v129
	v_mov_b32_e32 v26, v129
	v_mov_b32_e32 v17, v129
	v_mov_b32_e32 v16, v129
	v_mov_b32_e32 v15, v129
	v_mov_b32_e32 v14, v129
	v_mov_b32_e32 v13, v129
	v_mov_b32_e32 v12, v129
	v_mov_b32_e32 v11, v129
	v_mov_b32_e32 v10, v129
	v_mov_b32_e32 v57, v129
	v_mov_b32_e32 v56, v129
	v_mov_b32_e32 v55, v129
	v_mov_b32_e32 v54, v129
	v_mov_b32_e32 v53, v129
	v_mov_b32_e32 v52, v129
	v_mov_b32_e32 v51, v129
	v_mov_b32_e32 v50, v129
	v_mov_b32_e32 v41, v129
	v_mov_b32_e32 v40, v129
	v_mov_b32_e32 v39, v129
	v_mov_b32_e32 v38, v129
	v_mov_b32_e32 v37, v129
	v_mov_b32_e32 v36, v129
	v_mov_b32_e32 v35, v129
	v_mov_b32_e32 v34, v129
	v_mov_b32_e32 v25, v129
	v_mov_b32_e32 v24, v129
	v_mov_b32_e32 v23, v129
	v_mov_b32_e32 v22, v129
	v_mov_b32_e32 v21, v129
	v_mov_b32_e32 v20, v129
	v_mov_b32_e32 v19, v129
	v_mov_b32_e32 v18, v129
	v_mov_b32_e32 v9, v129
	v_mov_b32_e32 v8, v129
	v_mov_b32_e32 v7, v129
	v_mov_b32_e32 v6, v129
	v_mov_b32_e32 v5, v129
	v_mov_b32_e32 v4, v129
	v_mov_b32_e32 v3, v129
	v_mov_b32_e32 v2, v129
	s_cbranch_vccnz .LBB0_145
	s_and_b64 s[28:29], s[4:5], exec
	s_cselect_b32 s21, s27, s25
	s_cselect_b32 s23, s26, s24
	s_cselect_b32 s37, s43, s7
	s_cselect_b32 s38, s42, s6
	s_add_u32 s39, s6, 0x100
	s_addc_u32 s40, s7, 0
	s_add_u32 s6, s24, 0x40080
	v_mov_b32_e32 v2, 0
	s_addc_u32 s7, s25, 0
	s_mov_b32 s24, 0
.LBB0_143:
	s_add_i32 s41, s24, 2
	s_add_u32 s25, s6, 0xfffc0080
	s_addc_u32 s28, s7, -1
	s_add_i32 s49, 0, 0x10000
	s_cmp_eq_u32 s46, s24
	s_cselect_b32 s29, s21, s28
	s_cselect_b32 s28, s23, s25
	v_add_u32_e32 v144, s49, v146
	s_cselect_b32 s25, s37, s40
	s_cselect_b32 s24, s38, s39
	s_add_i32 s52, 0, 0x14000
	ds_read_b128 v[140:143], v144
	ds_read_b128 v[150:153], v144 offset:1024
	ds_read_b128 v[154:157], v144 offset:2048
	ds_read_b128 v[158:161], v144 offset:3072
	v_add_u32_e32 v144, s52, v146
	ds_read_b128 v[162:165], v144
	ds_read_b128 v[166:169], v144 offset:1024
	ds_read_b128 v[170:173], v144 offset:2048
	ds_read_b128 v[174:177], v144 offset:3072
	v_lshl_add_u64 v[190:191], s[6:7], 0, v[138:139]
	s_add_i32 m0, s18, 0xc000
	ds_read_b128 v[178:181], v149
	ds_read_b128 v[182:185], v149 offset:1024
	ds_read_b128 v[186:189], v149 offset:2048
	ds_read_b128 v[206:209], v149 offset:3072
	ds_read_b128 v[232:235], v149 offset:4096
	ds_read_b128 v[236:239], v149 offset:5120
	ds_read_b128 v[240:243], v149 offset:6144
	ds_read_b128 v[244:247], v149 offset:7168
	global_load_lds_dwordx4 v[190:191], off
	v_lshl_add_u64 v[190:191], s[6:7], 0, v[136:137]
	s_add_i32 m0, s18, 0xe000
	s_nop 0
	global_load_lds_dwordx4 v[190:191], off
	s_waitcnt vmcnt(8)
	s_waitcnt lgkmcnt(0)
	s_barrier
; #define PG8_STAGE(bufoff, gbase, voff) do { _Pragma("unroll") for (int _i = 0; _i < 2; ++_i) \
;         __builtin_amdgcn_global_load_lds((const unsigned*)((const char*)(gbase) + (voff)[_i]), (LAS unsigned*)(lds + (bufoff) + ldsw + _i * 8192), 16, 0, 0); } while (0)
; #define PG8_LDA(dst, b, h) do { _Pragma("unroll") for (int m = 0; m < 4; ++m) _Pragma("unroll") for (int k = 0; k < 2; ++k) dst[m][k] = *(const LAS bf16x8*)(lds + PG8_SA(b, h) + aoff + m * 2048 + k * 1024); } while (0)
; #define PG8_MMA(ai, bj, At, Bt) do { __builtin_amdgcn_s_setprio(1); _Pragma("unroll") for (int m = 0; m < 4; ++m) _Pragma("unroll") for (int n = 0; n < 2; ++n) _Pragma("unroll") for (int k = 0; k < 2; ++k) \
;         acc[ai][bj][m][n] = __builtin_amdgcn_mfma_f32_16x16x32_bf16(Bt[n][k], At[m][k], acc[ai][bj][m][n], 0, 0, 0); __builtin_amdgcn_s_setprio(0); } while (0)
; #define PG8_WAIT_V(n) asm volatile("s_waitcnt vmcnt(" #n ")" ::: "memory")
; #define PG8_WAIT_L(n) asm volatile("s_waitcnt lgkmcnt(" #n ")" ::: "memory")
; #define PG8_BAR __builtin_amdgcn_s_barrier()
; #define PG8_SCHED __builtin_amdgcn_sched_barrier(0)
; #define PG8_STAGE(bufoff, gbase, voff, q64) do { \
;         __builtin_amdgcn_global_load_lds((const unsigned*)((const char*)(gbase) + (voff)), (LAS unsigned*)(lds + (bufoff) + ldsw), 16, 0, 0); \
;         __builtin_amdgcn_global_load_lds((const unsigned*)((const char*)(gbase) + (q64) + (voff)), (LAS unsigned*)(lds + (bufoff) + ldsw + 8192), 16, 0, 0); } while (0)
; #define PG8_LDA(dst, b, h) do { _Pragma("unroll") for (int m = 0; m < 4; ++m) _Pragma("unroll") for (int k = 0; k < 2; ++k) dst[m][k] = *(const LAS bf16x8*)(lds + PG8_SA(b, h) + aoff + m * 2048 + k * 1024); } while (0)
; #define PG8_WAIT_V(n) asm volatile("s_waitcnt vmcnt(" #n ")" ::: "memory")
; #define PG8_BAR __builtin_amdgcn_s_barrier()
; template <class Epi, class Sched>
; __device__ __forceinline__ void gemm_phase(LAS unsigned char* lds, const Gemm g, const Sched S, const Epi E, const int tid) {
;     ...
;             PG8_WAIT_V(8); PG8_WAIT_L(0); PG8_BAR; PG8_MMA(0, 0, At, B0); PG8_MMA(0, 1, At, B1); PG8_BAR; PG8_SCHED;
;             PG8_LDA(At, 0, 1); PG8_STAGE(PG8_SB(0, 0), b2, voffB); PG8_STAGE(PG8_SB(0, 1), b2 + hstepB, voffB); PG8_STAGE(PG8_SA(0, 0), a2, voffA);
;             PG8_WAIT_V(8); PG8_WAIT_L(0); PG8_BAR; PG8_MMA(1, 0, At, B0); PG8_MMA(1, 1, At, B1); PG8_BAR; PG8_SCHED;
	s_setprio 1
	s_waitcnt lgkmcnt(0)
	v_mfma_f32_16x16x32_bf16 v[126:129], v[140:143], v[178:181], v[126:129]
	v_mfma_f32_16x16x32_bf16 v[122:125], v[154:157], v[178:181], v[122:125]
	v_mfma_f32_16x16x32_bf16 v[110:113], v[140:143], v[186:189], v[110:113]
	v_mfma_f32_16x16x32_bf16 v[106:109], v[154:157], v[186:189], v[106:109]
	v_mfma_f32_16x16x32_bf16 v[94:97], v[140:143], v[232:235], v[94:97]
	v_mfma_f32_16x16x32_bf16 v[90:93], v[154:157], v[232:235], v[90:93]
	v_mfma_f32_16x16x32_bf16 v[78:81], v[140:143], v[240:243], v[78:81]
	v_mfma_f32_16x16x32_bf16 v[74:77], v[154:157], v[240:243], v[74:77]
	v_mfma_f32_16x16x32_bf16 v[126:129], v[150:153], v[182:185], v[126:129]
	v_mfma_f32_16x16x32_bf16 v[122:125], v[158:161], v[182:185], v[122:125]
	v_mfma_f32_16x16x32_bf16 v[110:113], v[150:153], v[206:209], v[110:113]
	v_mfma_f32_16x16x32_bf16 v[106:109], v[158:161], v[206:209], v[106:109]
	v_mfma_f32_16x16x32_bf16 v[94:97], v[150:153], v[236:239], v[94:97]
	v_mfma_f32_16x16x32_bf16 v[90:93], v[158:161], v[236:239], v[90:93]
	v_mfma_f32_16x16x32_bf16 v[78:81], v[150:153], v[244:247], v[78:81]
	v_mfma_f32_16x16x32_bf16 v[74:77], v[158:161], v[244:247], v[74:77]
	s_setprio 0
	s_setprio 1
	v_mfma_f32_16x16x32_bf16 v[118:121], v[162:165], v[178:181], v[118:121]
	v_mfma_f32_16x16x32_bf16 v[114:117], v[170:173], v[178:181], v[114:117]
	v_mfma_f32_16x16x32_bf16 v[102:105], v[162:165], v[186:189], v[102:105]
	v_mfma_f32_16x16x32_bf16 v[98:101], v[170:173], v[186:189], v[98:101]
	v_mfma_f32_16x16x32_bf16 v[86:89], v[162:165], v[232:235], v[86:89]
	v_mfma_f32_16x16x32_bf16 v[82:85], v[170:173], v[232:235], v[82:85]
	v_mfma_f32_16x16x32_bf16 v[70:73], v[162:165], v[240:243], v[70:73]
	v_mfma_f32_16x16x32_bf16 v[66:69], v[170:173], v[240:243], v[66:69]
	v_mfma_f32_16x16x32_bf16 v[118:121], v[166:169], v[182:185], v[118:121]
	v_mfma_f32_16x16x32_bf16 v[114:117], v[174:177], v[182:185], v[114:117]
	v_mfma_f32_16x16x32_bf16 v[102:105], v[166:169], v[206:209], v[102:105]
	v_mfma_f32_16x16x32_bf16 v[98:101], v[174:177], v[206:209], v[98:101]
	v_mfma_f32_16x16x32_bf16 v[86:89], v[166:169], v[236:239], v[86:89]
	v_mfma_f32_16x16x32_bf16 v[82:85], v[174:177], v[236:239], v[82:85]
	v_mfma_f32_16x16x32_bf16 v[70:73], v[166:169], v[244:247], v[70:73]
	v_mfma_f32_16x16x32_bf16 v[66:69], v[174:177], v[244:247], v[66:69]
	s_setprio 0
	s_barrier
	s_add_i32 s49, s49, s15
	v_lshl_add_u64 v[190:191], s[24:25], 0, v[0:1]
	s_mov_b32 m0, s49
	ds_read_b128 v[178:181], v149 offset:16384
	ds_read_b128 v[182:185], v149 offset:17408
	ds_read_b128 v[186:189], v149 offset:18432
	ds_read_b128 v[206:209], v149 offset:19456
	ds_read_b128 v[232:235], v149 offset:20480
	ds_read_b128 v[236:239], v149 offset:21504
	ds_read_b128 v[240:243], v149 offset:22528
	ds_read_b128 v[244:247], v149 offset:23552
	global_load_lds_dwordx4 v[190:191], off
	s_add_i32 m0, s49, 0x2000
	s_add_u32 s50, s24, 0x40000
	v_lshl_add_u64 v[210:211], s[24:25], 0, v[134:135]
	s_addc_u32 s51, s25, 0
	s_add_i32 s49, s52, s15
	global_load_lds_dwordx4 v[210:211], off
	v_lshl_add_u64 v[218:219], s[50:51], 0, v[0:1]
	s_mov_b32 m0, s49
	v_lshl_add_u64 v[220:221], s[28:29], 0, v[132:133]
	global_load_lds_dwordx4 v[218:219], off
	v_lshl_add_u64 v[218:219], s[50:51], 0, v[134:135]
	s_add_i32 m0, s49, 0x2000
	s_nop 0
	global_load_lds_dwordx4 v[218:219], off
	v_lshl_add_u64 v[218:219], s[28:29], 0, v[130:131]
	s_mov_b32 m0, s18
	s_nop 0
	global_load_lds_dwordx4 v[218:219], off
	s_mov_b32 m0, s19
	s_nop 0
	global_load_lds_dwordx4 v[220:221], off
	s_waitcnt vmcnt(8)
	s_waitcnt lgkmcnt(0)
	s_barrier
	s_setprio 1
	s_waitcnt lgkmcnt(0)
	v_mfma_f32_16x16x32_bf16 v[62:65], v[140:143], v[178:181], v[62:65]
	v_mfma_f32_16x16x32_bf16 v[58:61], v[154:157], v[178:181], v[58:61]
	v_mfma_f32_16x16x32_bf16 v[46:49], v[140:143], v[186:189], v[46:49]
	v_mfma_f32_16x16x32_bf16 v[42:45], v[154:157], v[186:189], v[42:45]
	v_mfma_f32_16x16x32_bf16 v[30:33], v[140:143], v[232:235], v[30:33]
	v_mfma_f32_16x16x32_bf16 v[26:29], v[154:157], v[232:235], v[26:29]
	v_mfma_f32_16x16x32_bf16 v[14:17], v[140:143], v[240:243], v[14:17]
	v_mfma_f32_16x16x32_bf16 v[10:13], v[154:157], v[240:243], v[10:13]
	v_mfma_f32_16x16x32_bf16 v[62:65], v[150:153], v[182:185], v[62:65]
	v_mfma_f32_16x16x32_bf16 v[58:61], v[158:161], v[182:185], v[58:61]
	v_mfma_f32_16x16x32_bf16 v[46:49], v[150:153], v[206:209], v[46:49]
	v_mfma_f32_16x16x32_bf16 v[42:45], v[158:161], v[206:209], v[42:45]
	v_mfma_f32_16x16x32_bf16 v[30:33], v[150:153], v[236:239], v[30:33]
	v_mfma_f32_16x16x32_bf16 v[26:29], v[158:161], v[236:239], v[26:29]
	v_mfma_f32_16x16x32_bf16 v[14:17], v[150:153], v[244:247], v[14:17]
	v_mfma_f32_16x16x32_bf16 v[10:13], v[158:161], v[244:247], v[10:13]
	s_setprio 0
	s_setprio 1
	v_mfma_f32_16x16x32_bf16 v[54:57], v[162:165], v[178:181], v[54:57]
	v_mfma_f32_16x16x32_bf16 v[50:53], v[170:173], v[178:181], v[50:53]
	v_mfma_f32_16x16x32_bf16 v[38:41], v[162:165], v[186:189], v[38:41]
	v_mfma_f32_16x16x32_bf16 v[34:37], v[170:173], v[186:189], v[34:37]
	v_mfma_f32_16x16x32_bf16 v[22:25], v[162:165], v[232:235], v[22:25]
	v_mfma_f32_16x16x32_bf16 v[18:21], v[170:173], v[232:235], v[18:21]
	v_mfma_f32_16x16x32_bf16 v[6:9], v[162:165], v[240:243], v[6:9]
	v_mfma_f32_16x16x32_bf16 v[2:5], v[170:173], v[240:243], v[2:5]
	v_mfma_f32_16x16x32_bf16 v[54:57], v[166:169], v[182:185], v[54:57]
	v_mfma_f32_16x16x32_bf16 v[50:53], v[174:177], v[182:185], v[50:53]
	v_mfma_f32_16x16x32_bf16 v[38:41], v[166:169], v[206:209], v[38:41]
	v_mfma_f32_16x16x32_bf16 v[34:37], v[174:177], v[206:209], v[34:37]
	v_mfma_f32_16x16x32_bf16 v[22:25], v[166:169], v[236:239], v[22:25]
	v_mfma_f32_16x16x32_bf16 v[18:21], v[174:177], v[236:239], v[18:21]
	v_mfma_f32_16x16x32_bf16 v[6:9], v[166:169], v[244:247], v[6:9]
	v_mfma_f32_16x16x32_bf16 v[2:5], v[174:177], v[244:247], v[2:5]
	s_setprio 0
	s_barrier
; #define PG8_STAGE(bufoff, gbase, voff) do { _Pragma("unroll") for (int _i = 0; _i < 2; ++_i) \
;         __builtin_amdgcn_global_load_lds((const unsigned*)((const char*)(gbase) + (voff)[_i]), (LAS unsigned*)(lds + (bufoff) + ldsw + _i * 8192), 16, 0, 0); } while (0)
; #define PG8_LDA(dst, b, h) do { _Pragma("unroll") for (int m = 0; m < 4; ++m) _Pragma("unroll") for (int k = 0; k < 2; ++k) dst[m][k] = *(const LAS bf16x8*)(lds + PG8_SA(b, h) + aoff + m * 2048 + k * 1024); } while (0)
; #define PG8_LDB(dst, b, h) do { _Pragma("unroll") for (int n = 0; n < 2; ++n) _Pragma("unroll") for (int k = 0; k < 2; ++k) dst[n][k] = *(const LAS bf16x8*)(lds + PG8_SB(b, h) + boff + n * 2048 + k * 1024); } while (0)
; #define PG8_MMA(ai, bj, At, Bt) do { __builtin_amdgcn_s_setprio(1); _Pragma("unroll") for (int m = 0; m < 4; ++m) _Pragma("unroll") for (int n = 0; n < 2; ++n) _Pragma("unroll") for (int k = 0; k < 2; ++k) \
;         acc[ai][bj][m][n] = __builtin_amdgcn_mfma_f32_16x16x32_bf16(Bt[n][k], At[m][k], acc[ai][bj][m][n], 0, 0, 0); __builtin_amdgcn_s_setprio(0); } while (0)
; #define PG8_WAIT_V(n) asm volatile("s_waitcnt vmcnt(" #n ")" ::: "memory")
; #define PG8_WAIT_L(n) asm volatile("s_waitcnt lgkmcnt(" #n ")" ::: "memory")
; #define PG8_BAR __builtin_amdgcn_s_barrier()
; #define PG8_SCHED __builtin_amdgcn_sched_barrier(0)
; #define PG8_STAGE(bufoff, gbase, voff, q64) do { \
;         __builtin_amdgcn_global_load_lds((const unsigned*)((const char*)(gbase) + (voff)), (LAS unsigned*)(lds + (bufoff) + ldsw), 16, 0, 0); \
;         __builtin_amdgcn_global_load_lds((const unsigned*)((const char*)(gbase) + (q64) + (voff)), (LAS unsigned*)(lds + (bufoff) + ldsw + 8192), 16, 0, 0); } while (0)
; #define PG8_LDA(dst, b, h) do { _Pragma("unroll") for (int m = 0; m < 4; ++m) _Pragma("unroll") for (int k = 0; k < 2; ++k) dst[m][k] = *(const LAS bf16x8*)(lds + PG8_SA(b, h) + aoff + m * 2048 + k * 1024); } while (0)
; #define PG8_BAR __builtin_amdgcn_s_barrier()
; template <class Epi, class Sched>
; __device__ __forceinline__ void gemm_phase(LAS unsigned char* lds, const Gemm g, const Sched S, const Epi E, const int tid) {
;     ...
;             PG8_LDB(B0, 1, 0); PG8_LDB(B1, 1, 1); PG8_SCHED; PG8_LDA(At, 1, 0); PG8_STAGE(PG8_SA(0, 1), a2 + hstepA, voffA);
;             PG8_WAIT_V(8); PG8_WAIT_L(0); PG8_BAR; PG8_MMA(0, 0, At, B0); PG8_MMA(0, 1, At, B1); PG8_BAR; PG8_SCHED;
	s_add_i32 s49, 0, 0x18000
	v_add_u32_e32 v144, s49, v146
	s_add_i32 s50, 0, 0x1c000
	ds_read_b128 v[140:143], v144
	ds_read_b128 v[150:153], v144 offset:1024
	ds_read_b128 v[154:157], v144 offset:2048
	ds_read_b128 v[158:161], v144 offset:3072
	v_add_u32_e32 v144, s50, v146
	ds_read_b128 v[162:165], v144
	ds_read_b128 v[166:169], v144 offset:1024
	ds_read_b128 v[170:173], v144 offset:2048
	ds_read_b128 v[174:177], v144 offset:3072
	s_add_u32 s28, s28, 0x40000
	s_addc_u32 s29, s29, 0
	s_mov_b32 m0, s31
	v_lshl_add_u64 v[248:249], s[28:29], 0, v[130:131]
	ds_read_b128 v[178:181], v149 offset:32768
	ds_read_b128 v[182:185], v149 offset:33792
	ds_read_b128 v[186:189], v149 offset:34816
	ds_read_b128 v[206:209], v149 offset:35840
	ds_read_b128 v[232:235], v149 offset:36864
	ds_read_b128 v[236:239], v149 offset:37888
	ds_read_b128 v[240:243], v149 offset:38912
	ds_read_b128 v[244:247], v149 offset:39936
	global_load_lds_dwordx4 v[248:249], off
	v_lshl_add_u64 v[248:249], s[28:29], 0, v[132:133]
	s_mov_b32 m0, s34
	s_nop 0
	global_load_lds_dwordx4 v[248:249], off
	s_waitcnt vmcnt(8)
	s_waitcnt lgkmcnt(0)
	s_barrier
	s_setprio 1
	s_waitcnt lgkmcnt(0)
	v_mfma_f32_16x16x32_bf16 v[126:129], v[140:143], v[178:181], v[126:129]
	v_mfma_f32_16x16x32_bf16 v[122:125], v[154:157], v[178:181], v[122:125]
	v_mfma_f32_16x16x32_bf16 v[110:113], v[140:143], v[186:189], v[110:113]
	v_mfma_f32_16x16x32_bf16 v[106:109], v[154:157], v[186:189], v[106:109]
	v_mfma_f32_16x16x32_bf16 v[94:97], v[140:143], v[232:235], v[94:97]
	v_mfma_f32_16x16x32_bf16 v[90:93], v[154:157], v[232:235], v[90:93]
	v_mfma_f32_16x16x32_bf16 v[78:81], v[140:143], v[240:243], v[78:81]
	v_mfma_f32_16x16x32_bf16 v[74:77], v[154:157], v[240:243], v[74:77]
	v_mfma_f32_16x16x32_bf16 v[126:129], v[150:153], v[182:185], v[126:129]
	v_mfma_f32_16x16x32_bf16 v[122:125], v[158:161], v[182:185], v[122:125]
	v_mfma_f32_16x16x32_bf16 v[110:113], v[150:153], v[206:209], v[110:113]
	v_mfma_f32_16x16x32_bf16 v[106:109], v[158:161], v[206:209], v[106:109]
	v_mfma_f32_16x16x32_bf16 v[94:97], v[150:153], v[236:239], v[94:97]
	v_mfma_f32_16x16x32_bf16 v[90:93], v[158:161], v[236:239], v[90:93]
	v_mfma_f32_16x16x32_bf16 v[78:81], v[150:153], v[244:247], v[78:81]
	v_mfma_f32_16x16x32_bf16 v[74:77], v[158:161], v[244:247], v[74:77]
	s_setprio 0
	s_setprio 1
	v_mfma_f32_16x16x32_bf16 v[118:121], v[162:165], v[178:181], v[118:121]
	v_mfma_f32_16x16x32_bf16 v[114:117], v[170:173], v[178:181], v[114:117]
	v_mfma_f32_16x16x32_bf16 v[102:105], v[162:165], v[186:189], v[102:105]
	v_mfma_f32_16x16x32_bf16 v[98:101], v[170:173], v[186:189], v[98:101]
	v_mfma_f32_16x16x32_bf16 v[86:89], v[162:165], v[232:235], v[86:89]
	v_mfma_f32_16x16x32_bf16 v[82:85], v[170:173], v[232:235], v[82:85]
	v_mfma_f32_16x16x32_bf16 v[70:73], v[162:165], v[240:243], v[70:73]
	v_mfma_f32_16x16x32_bf16 v[66:69], v[170:173], v[240:243], v[66:69]
	v_mfma_f32_16x16x32_bf16 v[118:121], v[166:169], v[182:185], v[118:121]
	v_mfma_f32_16x16x32_bf16 v[114:117], v[174:177], v[182:185], v[114:117]
	v_mfma_f32_16x16x32_bf16 v[102:105], v[166:169], v[206:209], v[102:105]
	v_mfma_f32_16x16x32_bf16 v[98:101], v[174:177], v[206:209], v[98:101]
	v_mfma_f32_16x16x32_bf16 v[86:89], v[166:169], v[236:239], v[86:89]
	v_mfma_f32_16x16x32_bf16 v[82:85], v[174:177], v[236:239], v[82:85]
	v_mfma_f32_16x16x32_bf16 v[70:73], v[166:169], v[244:247], v[70:73]
	v_mfma_f32_16x16x32_bf16 v[66:69], v[174:177], v[244:247], v[66:69]
	s_setprio 0
	s_barrier
; #define PG8_STAGE(bufoff, gbase, voff) do { _Pragma("unroll") for (int _i = 0; _i < 2; ++_i) \
;         __builtin_amdgcn_global_load_lds((const unsigned*)((const char*)(gbase) + (voff)[_i]), (LAS unsigned*)(lds + (bufoff) + ldsw + _i * 8192), 16, 0, 0); } while (0)
; #define PG8_LDA(dst, b, h) do { _Pragma("unroll") for (int m = 0; m < 4; ++m) _Pragma("unroll") for (int k = 0; k < 2; ++k) dst[m][k] = *(const LAS bf16x8*)(lds + PG8_SA(b, h) + aoff + m * 2048 + k * 1024); } while (0)
; #define PG8_MMA(ai, bj, At, Bt) do { __builtin_amdgcn_s_setprio(1); _Pragma("unroll") for (int m = 0; m < 4; ++m) _Pragma("unroll") for (int n = 0; n < 2; ++n) _Pragma("unroll") for (int k = 0; k < 2; ++k) \
;         acc[ai][bj][m][n] = __builtin_amdgcn_mfma_f32_16x16x32_bf16(Bt[n][k], At[m][k], acc[ai][bj][m][n], 0, 0, 0); __builtin_amdgcn_s_setprio(0); } while (0)
; #define PG8_WAIT_V(n) asm volatile("s_waitcnt vmcnt(" #n ")" ::: "memory")
; #define PG8_WAIT_L(n) asm volatile("s_waitcnt lgkmcnt(" #n ")" ::: "memory")
; #define PG8_BAR __builtin_amdgcn_s_barrier()
; #define PG8_SCHED __builtin_amdgcn_sched_barrier(0)
; #define PG8_STAGE(bufoff, gbase, voff, q64) do { \
;         __builtin_amdgcn_global_load_lds((const unsigned*)((const char*)(gbase) + (voff)), (LAS unsigned*)(lds + (bufoff) + ldsw), 16, 0, 0); \
;         __builtin_amdgcn_global_load_lds((const unsigned*)((const char*)(gbase) + (q64) + (voff)), (LAS unsigned*)(lds + (bufoff) + ldsw + 8192), 16, 0, 0); } while (0)
; #define PG8_LDA(dst, b, h) do { _Pragma("unroll") for (int m = 0; m < 4; ++m) _Pragma("unroll") for (int k = 0; k < 2; ++k) dst[m][k] = *(const LAS bf16x8*)(lds + PG8_SA(b, h) + aoff + m * 2048 + k * 1024); } while (0)
; #define PG8_WAIT_V(n) asm volatile("s_waitcnt vmcnt(" #n ")" ::: "memory")
; #define PG8_WAIT_L(n) asm volatile("s_waitcnt lgkmcnt(" #n ")" ::: "memory")
; #define PG8_BAR __builtin_amdgcn_s_barrier()
; template <class Epi, class Sched>
; __device__ __forceinline__ void gemm_phase(LAS unsigned char* lds, const Gemm g, const Sched S, const Epi E, const int tid) {
;     ...
;             PG8_LDA(At, 1, 1); PG8_STAGE(PG8_SB(1, 0), b3, voffB); PG8_STAGE(PG8_SB(1, 1), b3 + hstepB, voffB); PG8_STAGE(PG8_SA(1, 0), a3, voffA);
;             PG8_WAIT_V(8); PG8_WAIT_L(0); PG8_BAR; PG8_MMA(1, 0, At, B0); PG8_MMA(1, 1, At, B1); PG8_BAR; PG8_SCHED;
;         }
	s_add_i32 s28, s49, s15
	v_lshl_add_u64 v[190:191], v[190:191], 0, s[0:1]
	s_mov_b32 m0, s28
	ds_read_b128 v[178:181], v149 offset:49152
	ds_read_b128 v[182:185], v149 offset:50176
	ds_read_b128 v[186:189], v149 offset:51200
	ds_read_b128 v[206:209], v149 offset:52224
	ds_read_b128 v[232:235], v149 offset:53248
	ds_read_b128 v[236:239], v149 offset:54272
	ds_read_b128 v[240:243], v149 offset:55296
	ds_read_b128 v[244:247], v149 offset:56320
	global_load_lds_dwordx4 v[190:191], off
	s_add_i32 m0, s28, 0x2000
	s_add_u32 s24, s24, 0x40080
	v_lshl_add_u64 v[190:191], v[210:211], 0, s[0:1]
	s_addc_u32 s25, s25, 0
	s_add_i32 s28, s50, s15
	global_load_lds_dwordx4 v[190:191], off
	v_lshl_add_u64 v[190:191], s[24:25], 0, v[0:1]
	s_mov_b32 m0, s28
	s_nop 0
	global_load_lds_dwordx4 v[190:191], off
	v_lshl_add_u64 v[190:191], s[24:25], 0, v[134:135]
	s_add_i32 m0, s28, 0x2000
	s_nop 0
	global_load_lds_dwordx4 v[190:191], off
	v_lshl_add_u64 v[190:191], v[218:219], 0, s[0:1]
	s_mov_b32 m0, s44
	s_nop 0
	global_load_lds_dwordx4 v[190:191], off
	v_lshl_add_u64 v[190:191], v[220:221], 0, s[0:1]
	s_mov_b32 m0, s45
	s_nop 0
	global_load_lds_dwordx4 v[190:191], off
	s_waitcnt vmcnt(8)
	s_waitcnt lgkmcnt(0)
	s_barrier
	s_setprio 1
	s_waitcnt lgkmcnt(0)
	v_mfma_f32_16x16x32_bf16 v[62:65], v[140:143], v[178:181], v[62:65]
	v_mfma_f32_16x16x32_bf16 v[58:61], v[154:157], v[178:181], v[58:61]
	v_mfma_f32_16x16x32_bf16 v[46:49], v[140:143], v[186:189], v[46:49]
	v_mfma_f32_16x16x32_bf16 v[42:45], v[154:157], v[186:189], v[42:45]
	v_mfma_f32_16x16x32_bf16 v[30:33], v[140:143], v[232:235], v[30:33]
	v_mfma_f32_16x16x32_bf16 v[26:29], v[154:157], v[232:235], v[26:29]
	v_mfma_f32_16x16x32_bf16 v[14:17], v[140:143], v[240:243], v[14:17]
	v_mfma_f32_16x16x32_bf16 v[10:13], v[154:157], v[240:243], v[10:13]
	v_mfma_f32_16x16x32_bf16 v[62:65], v[150:153], v[182:185], v[62:65]
	v_mfma_f32_16x16x32_bf16 v[58:61], v[158:161], v[182:185], v[58:61]
	v_mfma_f32_16x16x32_bf16 v[46:49], v[150:153], v[206:209], v[46:49]
	v_mfma_f32_16x16x32_bf16 v[42:45], v[158:161], v[206:209], v[42:45]
	v_mfma_f32_16x16x32_bf16 v[30:33], v[150:153], v[236:239], v[30:33]
	v_mfma_f32_16x16x32_bf16 v[26:29], v[158:161], v[236:239], v[26:29]
	v_mfma_f32_16x16x32_bf16 v[14:17], v[150:153], v[244:247], v[14:17]
	v_mfma_f32_16x16x32_bf16 v[10:13], v[158:161], v[244:247], v[10:13]
	s_setprio 0
	s_setprio 1
	v_mfma_f32_16x16x32_bf16 v[54:57], v[162:165], v[178:181], v[54:57]
	v_mfma_f32_16x16x32_bf16 v[50:53], v[170:173], v[178:181], v[50:53]
	v_mfma_f32_16x16x32_bf16 v[38:41], v[162:165], v[186:189], v[38:41]
	v_mfma_f32_16x16x32_bf16 v[34:37], v[170:173], v[186:189], v[34:37]
	v_mfma_f32_16x16x32_bf16 v[22:25], v[162:165], v[232:235], v[22:25]
	v_mfma_f32_16x16x32_bf16 v[18:21], v[170:173], v[232:235], v[18:21]
	v_mfma_f32_16x16x32_bf16 v[6:9], v[162:165], v[240:243], v[6:9]
	v_mfma_f32_16x16x32_bf16 v[2:5], v[170:173], v[240:243], v[2:5]
	v_mfma_f32_16x16x32_bf16 v[54:57], v[166:169], v[182:185], v[54:57]
	v_mfma_f32_16x16x32_bf16 v[50:53], v[174:177], v[182:185], v[50:53]
	v_mfma_f32_16x16x32_bf16 v[38:41], v[166:169], v[206:209], v[38:41]
	v_mfma_f32_16x16x32_bf16 v[34:37], v[174:177], v[206:209], v[34:37]
	v_mfma_f32_16x16x32_bf16 v[22:25], v[166:169], v[236:239], v[22:25]
	v_mfma_f32_16x16x32_bf16 v[18:21], v[174:177], v[236:239], v[18:21]
	v_mfma_f32_16x16x32_bf16 v[6:9], v[166:169], v[244:247], v[6:9]
	v_mfma_f32_16x16x32_bf16 v[2:5], v[174:177], v[244:247], v[2:5]
	s_setprio 0
	s_barrier
	s_add_u32 s39, s39, 0x100
	s_addc_u32 s40, s40, 0
	s_add_u32 s6, s6, 0x100
	s_addc_u32 s7, s7, 0
	s_cmp_ge_i32 s41, s35
	s_mov_b32 s24, s41
	s_cbranch_scc0 .LBB0_143
	v_readlane_b32 s38, v254, 48
	v_readlane_b32 s39, v254, 49

; #define PG8_STAGE(bufoff, gbase, voff) do { _Pragma("unroll") for (int _i = 0; _i < 2; ++_i) \
;         __builtin_amdgcn_global_load_lds((const unsigned*)((const char*)(gbase) + (voff)[_i]), (LAS unsigned*)(lds + (bufoff) + ldsw + _i * 8192), 16, 0, 0); } while (0)
; #define PG8_LDA(dst, b, h) do { _Pragma("unroll") for (int m = 0; m < 4; ++m) _Pragma("unroll") for (int k = 0; k < 2; ++k) dst[m][k] = *(const LAS bf16x8*)(lds + PG8_SA(b, h) + aoff + m * 2048 + k * 1024); } while (0)
; #define PG8_LDB(dst, b, h) do { _Pragma("unroll") for (int n = 0; n < 2; ++n) _Pragma("unroll") for (int k = 0; k < 2; ++k) dst[n][k] = *(const LAS bf16x8*)(lds + PG8_SB(b, h) + boff + n * 2048 + k * 1024); } while (0)
; #define PG8_SCHED __builtin_amdgcn_sched_barrier(0)
; #define PG8_STAGE(bufoff, gbase, voff, q64) do { \
;         __builtin_amdgcn_global_load_lds((const unsigned*)((const char*)(gbase) + (voff)), (LAS unsigned*)(lds + (bufoff) + ldsw), 16, 0, 0); \
;         __builtin_amdgcn_global_load_lds((const unsigned*)((const char*)(gbase) + (q64) + (voff)), (LAS unsigned*)(lds + (bufoff) + ldsw + 8192), 16, 0, 0); } while (0)
; #define PG8_SCHED __builtin_amdgcn_sched_barrier(0)
; template <class Epi, class Sched>
; __device__ __forceinline__ void gemm_phase(LAS unsigned char* lds, const Gemm g, const Sched S, const Epi E, const int tid) {
;     ...
;         const bool has_next = S.next(ui + 1, nxt);
;         const char* nA = has_next ? (const char*)g.A + (size_t)nxt.pm * tstepA : cA; const char* nB = has_next ? (const char*)g.Bt + (size_t)nxt.pn * tstepB : cB;
;         for (int t = 0; t < nt; t += 2) {
;             const bool last = (t == nt - 2);
;             const char* a1 = cA + (size_t)(t + 1) * kstep;
;             const char* a2 = last ? nA : cA + (size_t)(t + 2) * kstep; const char* b2 = last ? nB : cB + (size_t)(t + 2) * kstep;
;             const char* a3 = a2 + kstep; const char* b3 = b2 + kstep;
;             PG8_LDB(B0, 0, 0); PG8_LDB(B1, 0, 1); PG8_SCHED; PG8_LDA(At, 0, 0); PG8_STAGE(PG8_SA(1, 1), a1 + hstepA, voffA);
;     ...
; #pragma unroll
;         for (int a = 0; a < 2; ++a)
; #pragma unroll
;             for (int b = 0; b < 2; ++b)
; #pragma unroll
;                 for (int m = 0; m < 4; ++m)
; #pragma unroll
;                     for (int n = 0; n < 2; ++n) acc[a][b][m][n] = (f32x4){0.f, 0.f, 0.f, 0.f};
;         cur = nxt; cA = nA; cB = nB; ++ui;
.LBB0_546:
	s_ashr_i32 s53, s52, 31
	s_lshl_b64 s[12:13], s[52:53], 19
	s_add_u32 s64, s36, s12
	s_addc_u32 s65, s37, s13
	s_ashr_i32 s51, s50, 31
	s_lshl_b64 s[12:13], s[50:51], 19
	s_add_u32 s68, s61, s12
	v_mov_b32_e32 v129, 0
	s_addc_u32 s69, s70, s13
	s_andn2_b64 vcc, exec, s[10:11]
	v_mov_b32_e32 v128, v129
	v_mov_b32_e32 v127, v129
	v_mov_b32_e32 v126, v129
	v_mov_b32_e32 v125, v129
	v_mov_b32_e32 v124, v129
	v_mov_b32_e32 v123, v129
	v_mov_b32_e32 v122, v129
	v_mov_b32_e32 v113, v129
	v_mov_b32_e32 v112, v129
	v_mov_b32_e32 v111, v129
	v_mov_b32_e32 v110, v129
	v_mov_b32_e32 v109, v129
	v_mov_b32_e32 v108, v129
	v_mov_b32_e32 v107, v129
	v_mov_b32_e32 v106, v129
	v_mov_b32_e32 v97, v129
	v_mov_b32_e32 v96, v129
	v_mov_b32_e32 v95, v129
	v_mov_b32_e32 v94, v129
	v_mov_b32_e32 v93, v129
	v_mov_b32_e32 v92, v129
	v_mov_b32_e32 v91, v129
	v_mov_b32_e32 v90, v129
	v_mov_b32_e32 v81, v129
	v_mov_b32_e32 v80, v129
	v_mov_b32_e32 v79, v129
	v_mov_b32_e32 v78, v129
	v_mov_b32_e32 v77, v129
	v_mov_b32_e32 v76, v129
	v_mov_b32_e32 v75, v129
	v_mov_b32_e32 v74, v129
	v_mov_b32_e32 v121, v129
	v_mov_b32_e32 v120, v129
	v_mov_b32_e32 v119, v129
	v_mov_b32_e32 v118, v129
	v_mov_b32_e32 v117, v129
	v_mov_b32_e32 v116, v129
	v_mov_b32_e32 v115, v129
	v_mov_b32_e32 v114, v129
	v_mov_b32_e32 v105, v129
	v_mov_b32_e32 v104, v129
	v_mov_b32_e32 v103, v129
	v_mov_b32_e32 v102, v129
	v_mov_b32_e32 v101, v129
	v_mov_b32_e32 v100, v129
	v_mov_b32_e32 v99, v129
	v_mov_b32_e32 v98, v129
	v_mov_b32_e32 v89, v129
	v_mov_b32_e32 v88, v129
	v_mov_b32_e32 v87, v129
	v_mov_b32_e32 v86, v129
	v_mov_b32_e32 v85, v129
	v_mov_b32_e32 v84, v129
	v_mov_b32_e32 v83, v129
	v_mov_b32_e32 v82, v129
	v_mov_b32_e32 v73, v129
	v_mov_b32_e32 v72, v129
	v_mov_b32_e32 v71, v129
	v_mov_b32_e32 v70, v129
	v_mov_b32_e32 v69, v129
	v_mov_b32_e32 v68, v129
	v_mov_b32_e32 v67, v129
	v_mov_b32_e32 v66, v129
	v_mov_b32_e32 v65, v129
	v_mov_b32_e32 v64, v129
	v_mov_b32_e32 v63, v129
	v_mov_b32_e32 v62, v129
	v_mov_b32_e32 v61, v129
	v_mov_b32_e32 v60, v129
	v_mov_b32_e32 v59, v129
	v_mov_b32_e32 v58, v129
	v_mov_b32_e32 v49, v129
	v_mov_b32_e32 v48, v129
	v_mov_b32_e32 v47, v129
	v_mov_b32_e32 v46, v129
	v_mov_b32_e32 v45, v129
	v_mov_b32_e32 v44, v129
	v_mov_b32_e32 v43, v129
	v_mov_b32_e32 v42, v129
	v_mov_b32_e32 v33, v129
	v_mov_b32_e32 v32, v129
	v_mov_b32_e32 v31, v129
	v_mov_b32_e32 v30, v129
	v_mov_b32_e32 v29, v129
	v_mov_b32_e32 v28, v129
	v_mov_b32_e32 v27, v129
	v_mov_b32_e32 v26, v129
	v_mov_b32_e32 v17, v129
	v_mov_b32_e32 v16, v129
	v_mov_b32_e32 v15, v129
	v_mov_b32_e32 v14, v129
	v_mov_b32_e32 v13, v129
	v_mov_b32_e32 v12, v129
	v_mov_b32_e32 v11, v129
	v_mov_b32_e32 v10, v129
	v_mov_b32_e32 v57, v129
	v_mov_b32_e32 v56, v129
	v_mov_b32_e32 v55, v129
	v_mov_b32_e32 v54, v129
	v_mov_b32_e32 v53, v129
	v_mov_b32_e32 v52, v129
	v_mov_b32_e32 v51, v129
	v_mov_b32_e32 v50, v129
	v_mov_b32_e32 v41, v129
	v_mov_b32_e32 v40, v129
	v_mov_b32_e32 v39, v129
	v_mov_b32_e32 v38, v129
	v_mov_b32_e32 v37, v129
	v_mov_b32_e32 v36, v129
	v_mov_b32_e32 v35, v129
	v_mov_b32_e32 v34, v129
	v_mov_b32_e32 v25, v129
	v_mov_b32_e32 v24, v129
	v_mov_b32_e32 v23, v129
	v_mov_b32_e32 v22, v129
	v_mov_b32_e32 v21, v129
	v_mov_b32_e32 v20, v129
	v_mov_b32_e32 v19, v129
	v_mov_b32_e32 v18, v129
	v_mov_b32_e32 v9, v129
	v_mov_b32_e32 v8, v129
	v_mov_b32_e32 v7, v129
	v_mov_b32_e32 v6, v129
	v_mov_b32_e32 v5, v129
	v_mov_b32_e32 v4, v129
	v_mov_b32_e32 v3, v129
	v_mov_b32_e32 v2, v129
	s_cbranch_vccnz .LBB0_549
	s_and_b64 s[12:13], s[44:45], exec
	s_cselect_b32 s12, s65, s7
	s_cselect_b32 s13, s64, s6
	s_cselect_b32 s14, s69, s5
	s_cselect_b32 s15, s68, s4
	s_add_u32 s18, s4, 0x100
	s_addc_u32 s19, s5, 0
	s_add_u32 s4, s6, 0x40080
	v_mov_b32_e32 v2, 0
	s_addc_u32 s5, s7, 0
	s_mov_b32 s6, 0
.LBB0_548:
	s_add_i32 s20, s6, 2
	s_add_u32 s7, s4, 0xfffc0080
	s_addc_u32 s16, s5, -1
	s_add_i32 s21, 0, 0x10000
	s_cmp_eq_u32 s80, s6
	s_cselect_b32 s17, s12, s16
	s_cselect_b32 s16, s13, s7
	v_add_u32_e32 v0, s21, v177
	s_cselect_b32 s7, s14, s19
	s_cselect_b32 s6, s15, s18
	s_add_i32 s24, 0, 0x14000
	ds_read_b128 v[150:153], v0
	ds_read_b128 v[154:157], v0 offset:1024
	ds_read_b128 v[158:161], v0 offset:2048
	ds_read_b128 v[162:165], v0 offset:3072
	v_add_u32_e32 v0, s24, v177
	ds_read_b128 v[166:169], v0
	ds_read_b128 v[170:173], v0 offset:1024
	ds_read_b128 v[180:183], v0 offset:2048
	ds_read_b128 v[184:187], v0 offset:3072
	v_lshl_add_u64 v[174:175], s[4:5], 0, v[148:149]
	s_add_i32 m0, s72, 0xc000
	ds_read_b128 v[206:209], v179
	ds_read_b128 v[232:235], v179 offset:1024
	ds_read_b128 v[236:239], v179 offset:2048
	ds_read_b128 v[240:243], v179 offset:3072
	ds_read_b128 v[244:247], v179 offset:4096
	ds_read_b128 v[248:251], v179 offset:5120
	ds_read_b128 v[188:191], v179 offset:6144
	ds_read_b128 v[218:221], v179 offset:7168
	global_load_lds_dwordx4 v[174:175], off
	v_lshl_add_u64 v[174:175], s[4:5], 0, v[146:147]
	s_add_i32 m0, s72, 0xe000
	s_nop 0
	global_load_lds_dwordx4 v[174:175], off
	s_waitcnt vmcnt(8)
	s_waitcnt lgkmcnt(0)
	s_barrier
; #define PG8_STAGE(bufoff, gbase, voff) do { _Pragma("unroll") for (int _i = 0; _i < 2; ++_i) \
;         __builtin_amdgcn_global_load_lds((const unsigned*)((const char*)(gbase) + (voff)[_i]), (LAS unsigned*)(lds + (bufoff) + ldsw + _i * 8192), 16, 0, 0); } while (0)
; #define PG8_LDA(dst, b, h) do { _Pragma("unroll") for (int m = 0; m < 4; ++m) _Pragma("unroll") for (int k = 0; k < 2; ++k) dst[m][k] = *(const LAS bf16x8*)(lds + PG8_SA(b, h) + aoff + m * 2048 + k * 1024); } while (0)
; #define PG8_MMA(ai, bj, At, Bt) do { __builtin_amdgcn_s_setprio(1); _Pragma("unroll") for (int m = 0; m < 4; ++m) _Pragma("unroll") for (int n = 0; n < 2; ++n) _Pragma("unroll") for (int k = 0; k < 2; ++k) \
;         acc[ai][bj][m][n] = __builtin_amdgcn_mfma_f32_16x16x32_bf16(Bt[n][k], At[m][k], acc[ai][bj][m][n], 0, 0, 0); __builtin_amdgcn_s_setprio(0); } while (0)
; #define PG8_WAIT_V(n) asm volatile("s_waitcnt vmcnt(" #n ")" ::: "memory")
; #define PG8_WAIT_L(n) asm volatile("s_waitcnt lgkmcnt(" #n ")" ::: "memory")
; #define PG8_BAR __builtin_amdgcn_s_barrier()
; #define PG8_SCHED __builtin_amdgcn_sched_barrier(0)
; #define PG8_STAGE(bufoff, gbase, voff, q64) do { \
;         __builtin_amdgcn_global_load_lds((const unsigned*)((const char*)(gbase) + (voff)), (LAS unsigned*)(lds + (bufoff) + ldsw), 16, 0, 0); \
;         __builtin_amdgcn_global_load_lds((const unsigned*)((const char*)(gbase) + (q64) + (voff)), (LAS unsigned*)(lds + (bufoff) + ldsw + 8192), 16, 0, 0); } while (0)
; #define PG8_LDA(dst, b, h) do { _Pragma("unroll") for (int m = 0; m < 4; ++m) _Pragma("unroll") for (int k = 0; k < 2; ++k) dst[m][k] = *(const LAS bf16x8*)(lds + PG8_SA(b, h) + aoff + m * 2048 + k * 1024); } while (0)
; #define PG8_WAIT_V(n) asm volatile("s_waitcnt vmcnt(" #n ")" ::: "memory")
; #define PG8_BAR __builtin_amdgcn_s_barrier()
; template <class Epi, class Sched>
; __device__ __forceinline__ void gemm_phase(LAS unsigned char* lds, const Gemm g, const Sched S, const Epi E, const int tid) {
;     ...
;             PG8_WAIT_V(8); PG8_WAIT_L(0); PG8_BAR; PG8_MMA(0, 0, At, B0); PG8_MMA(0, 1, At, B1); PG8_BAR; PG8_SCHED;
;             PG8_LDA(At, 0, 1); PG8_STAGE(PG8_SB(0, 0), b2, voffB); PG8_STAGE(PG8_SB(0, 1), b2 + hstepB, voffB); PG8_STAGE(PG8_SA(0, 0), a2, voffA);
;             PG8_WAIT_V(8); PG8_WAIT_L(0); PG8_BAR; PG8_MMA(1, 0, At, B0); PG8_MMA(1, 1, At, B1); PG8_BAR; PG8_SCHED;
	s_setprio 1
	s_waitcnt lgkmcnt(0)
	v_mfma_f32_16x16x32_bf16 v[126:129], v[150:153], v[206:209], v[126:129]
	v_mfma_f32_16x16x32_bf16 v[122:125], v[158:161], v[206:209], v[122:125]
	v_mfma_f32_16x16x32_bf16 v[110:113], v[150:153], v[236:239], v[110:113]
	v_mfma_f32_16x16x32_bf16 v[106:109], v[158:161], v[236:239], v[106:109]
	v_mfma_f32_16x16x32_bf16 v[94:97], v[150:153], v[244:247], v[94:97]
	v_mfma_f32_16x16x32_bf16 v[90:93], v[158:161], v[244:247], v[90:93]
	v_mfma_f32_16x16x32_bf16 v[78:81], v[150:153], v[188:191], v[78:81]
	v_mfma_f32_16x16x32_bf16 v[74:77], v[158:161], v[188:191], v[74:77]
	v_mfma_f32_16x16x32_bf16 v[126:129], v[154:157], v[232:235], v[126:129]
	v_mfma_f32_16x16x32_bf16 v[122:125], v[162:165], v[232:235], v[122:125]
	v_mfma_f32_16x16x32_bf16 v[110:113], v[154:157], v[240:243], v[110:113]
	v_mfma_f32_16x16x32_bf16 v[106:109], v[162:165], v[240:243], v[106:109]
	v_mfma_f32_16x16x32_bf16 v[94:97], v[154:157], v[248:251], v[94:97]
	v_mfma_f32_16x16x32_bf16 v[90:93], v[162:165], v[248:251], v[90:93]
	v_mfma_f32_16x16x32_bf16 v[78:81], v[154:157], v[218:221], v[78:81]
	v_mfma_f32_16x16x32_bf16 v[74:77], v[162:165], v[218:221], v[74:77]
	s_setprio 0
	s_setprio 1
	v_mfma_f32_16x16x32_bf16 v[118:121], v[166:169], v[206:209], v[118:121]
	v_mfma_f32_16x16x32_bf16 v[114:117], v[180:183], v[206:209], v[114:117]
	v_mfma_f32_16x16x32_bf16 v[102:105], v[166:169], v[236:239], v[102:105]
	v_mfma_f32_16x16x32_bf16 v[98:101], v[180:183], v[236:239], v[98:101]
	v_mfma_f32_16x16x32_bf16 v[86:89], v[166:169], v[244:247], v[86:89]
	v_mfma_f32_16x16x32_bf16 v[82:85], v[180:183], v[244:247], v[82:85]
	v_mfma_f32_16x16x32_bf16 v[70:73], v[166:169], v[188:191], v[70:73]
	v_mfma_f32_16x16x32_bf16 v[66:69], v[180:183], v[188:191], v[66:69]
	v_mfma_f32_16x16x32_bf16 v[118:121], v[170:173], v[232:235], v[118:121]
	v_mfma_f32_16x16x32_bf16 v[114:117], v[184:187], v[232:235], v[114:117]
	v_mfma_f32_16x16x32_bf16 v[102:105], v[170:173], v[240:243], v[102:105]
	v_mfma_f32_16x16x32_bf16 v[98:101], v[184:187], v[240:243], v[98:101]
	v_mfma_f32_16x16x32_bf16 v[86:89], v[170:173], v[248:251], v[86:89]
	v_mfma_f32_16x16x32_bf16 v[82:85], v[184:187], v[248:251], v[82:85]
	v_mfma_f32_16x16x32_bf16 v[70:73], v[170:173], v[218:221], v[70:73]
	v_mfma_f32_16x16x32_bf16 v[66:69], v[184:187], v[218:221], v[66:69]
	s_setprio 0
	s_barrier
	s_add_i32 s21, s21, s71
	v_lshl_add_u64 v[174:175], s[6:7], 0, v[132:133]
	s_mov_b32 m0, s21
	ds_read_b128 v[188:191], v179 offset:16384
	ds_read_b128 v[206:209], v179 offset:17408
	ds_read_b128 v[218:221], v179 offset:18432
	ds_read_b128 v[232:235], v179 offset:19456
	ds_read_b128 v[236:239], v179 offset:20480
	ds_read_b128 v[240:243], v179 offset:21504
	ds_read_b128 v[244:247], v179 offset:22528
	ds_read_b128 v[248:251], v179 offset:23552
	global_load_lds_dwordx4 v[174:175], off
	s_add_i32 m0, s21, 0x2000
	s_add_u32 s22, s6, 0x40000
	v_lshl_add_u64 v[192:193], s[6:7], 0, v[136:137]
	s_addc_u32 s23, s7, 0
	s_add_i32 s21, s24, s71
	global_load_lds_dwordx4 v[192:193], off
	v_lshl_add_u64 v[194:195], s[22:23], 0, v[132:133]
	s_mov_b32 m0, s21
	v_lshl_add_u64 v[210:211], s[16:17], 0, v[134:135]
	global_load_lds_dwordx4 v[194:195], off
	v_lshl_add_u64 v[194:195], s[22:23], 0, v[136:137]
	s_add_i32 m0, s21, 0x2000
	s_nop 0
	global_load_lds_dwordx4 v[194:195], off
	v_lshl_add_u64 v[194:195], s[16:17], 0, v[130:131]
	s_mov_b32 m0, s72
	s_nop 0
	global_load_lds_dwordx4 v[194:195], off
	s_mov_b32 m0, s73
	s_nop 0
	global_load_lds_dwordx4 v[210:211], off
	s_waitcnt vmcnt(8)
	s_waitcnt lgkmcnt(0)
	s_barrier
	s_setprio 1
	s_waitcnt lgkmcnt(0)
	v_mfma_f32_16x16x32_bf16 v[62:65], v[150:153], v[188:191], v[62:65]
	v_mfma_f32_16x16x32_bf16 v[58:61], v[158:161], v[188:191], v[58:61]
	v_mfma_f32_16x16x32_bf16 v[46:49], v[150:153], v[218:221], v[46:49]
	v_mfma_f32_16x16x32_bf16 v[42:45], v[158:161], v[218:221], v[42:45]
	v_mfma_f32_16x16x32_bf16 v[30:33], v[150:153], v[236:239], v[30:33]
	v_mfma_f32_16x16x32_bf16 v[26:29], v[158:161], v[236:239], v[26:29]
	v_mfma_f32_16x16x32_bf16 v[14:17], v[150:153], v[244:247], v[14:17]
	v_mfma_f32_16x16x32_bf16 v[10:13], v[158:161], v[244:247], v[10:13]
	v_mfma_f32_16x16x32_bf16 v[62:65], v[154:157], v[206:209], v[62:65]
	v_mfma_f32_16x16x32_bf16 v[58:61], v[162:165], v[206:209], v[58:61]
	v_mfma_f32_16x16x32_bf16 v[46:49], v[154:157], v[232:235], v[46:49]
	v_mfma_f32_16x16x32_bf16 v[42:45], v[162:165], v[232:235], v[42:45]
	v_mfma_f32_16x16x32_bf16 v[30:33], v[154:157], v[240:243], v[30:33]
	v_mfma_f32_16x16x32_bf16 v[26:29], v[162:165], v[240:243], v[26:29]
	v_mfma_f32_16x16x32_bf16 v[14:17], v[154:157], v[248:251], v[14:17]
	v_mfma_f32_16x16x32_bf16 v[10:13], v[162:165], v[248:251], v[10:13]
	s_setprio 0
	s_setprio 1
	v_mfma_f32_16x16x32_bf16 v[54:57], v[166:169], v[188:191], v[54:57]
	v_mfma_f32_16x16x32_bf16 v[50:53], v[180:183], v[188:191], v[50:53]
	v_mfma_f32_16x16x32_bf16 v[38:41], v[166:169], v[218:221], v[38:41]
	v_mfma_f32_16x16x32_bf16 v[34:37], v[180:183], v[218:221], v[34:37]
	v_mfma_f32_16x16x32_bf16 v[22:25], v[166:169], v[236:239], v[22:25]
	v_mfma_f32_16x16x32_bf16 v[18:21], v[180:183], v[236:239], v[18:21]
	v_mfma_f32_16x16x32_bf16 v[6:9], v[166:169], v[244:247], v[6:9]
	v_mfma_f32_16x16x32_bf16 v[2:5], v[180:183], v[244:247], v[2:5]
	v_mfma_f32_16x16x32_bf16 v[54:57], v[170:173], v[206:209], v[54:57]
	v_mfma_f32_16x16x32_bf16 v[50:53], v[184:187], v[206:209], v[50:53]
	v_mfma_f32_16x16x32_bf16 v[38:41], v[170:173], v[232:235], v[38:41]
	v_mfma_f32_16x16x32_bf16 v[34:37], v[184:187], v[232:235], v[34:37]
	v_mfma_f32_16x16x32_bf16 v[22:25], v[170:173], v[240:243], v[22:25]
	v_mfma_f32_16x16x32_bf16 v[18:21], v[184:187], v[240:243], v[18:21]
	v_mfma_f32_16x16x32_bf16 v[6:9], v[170:173], v[248:251], v[6:9]
	v_mfma_f32_16x16x32_bf16 v[2:5], v[184:187], v[248:251], v[2:5]
	s_setprio 0
	s_barrier
; #define PG8_STAGE(bufoff, gbase, voff) do { _Pragma("unroll") for (int _i = 0; _i < 2; ++_i) \
;         __builtin_amdgcn_global_load_lds((const unsigned*)((const char*)(gbase) + (voff)[_i]), (LAS unsigned*)(lds + (bufoff) + ldsw + _i * 8192), 16, 0, 0); } while (0)
; #define PG8_LDA(dst, b, h) do { _Pragma("unroll") for (int m = 0; m < 4; ++m) _Pragma("unroll") for (int k = 0; k < 2; ++k) dst[m][k] = *(const LAS bf16x8*)(lds + PG8_SA(b, h) + aoff + m * 2048 + k * 1024); } while (0)
; #define PG8_LDB(dst, b, h) do { _Pragma("unroll") for (int n = 0; n < 2; ++n) _Pragma("unroll") for (int k = 0; k < 2; ++k) dst[n][k] = *(const LAS bf16x8*)(lds + PG8_SB(b, h) + boff + n * 2048 + k * 1024); } while (0)
; #define PG8_MMA(ai, bj, At, Bt) do { __builtin_amdgcn_s_setprio(1); _Pragma("unroll") for (int m = 0; m < 4; ++m) _Pragma("unroll") for (int n = 0; n < 2; ++n) _Pragma("unroll") for (int k = 0; k < 2; ++k) \
;         acc[ai][bj][m][n] = __builtin_amdgcn_mfma_f32_16x16x32_bf16(Bt[n][k], At[m][k], acc[ai][bj][m][n], 0, 0, 0); __builtin_amdgcn_s_setprio(0); } while (0)
; #define PG8_WAIT_V(n) asm volatile("s_waitcnt vmcnt(" #n ")" ::: "memory")
; #define PG8_WAIT_L(n) asm volatile("s_waitcnt lgkmcnt(" #n ")" ::: "memory")
; #define PG8_BAR __builtin_amdgcn_s_barrier()
; #define PG8_SCHED __builtin_amdgcn_sched_barrier(0)
; #define PG8_STAGE(bufoff, gbase, voff, q64) do { \
;         __builtin_amdgcn_global_load_lds((const unsigned*)((const char*)(gbase) + (voff)), (LAS unsigned*)(lds + (bufoff) + ldsw), 16, 0, 0); \
;         __builtin_amdgcn_global_load_lds((const unsigned*)((const char*)(gbase) + (q64) + (voff)), (LAS unsigned*)(lds + (bufoff) + ldsw + 8192), 16, 0, 0); } while (0)
; #define PG8_LDA(dst, b, h) do { _Pragma("unroll") for (int m = 0; m < 4; ++m) _Pragma("unroll") for (int k = 0; k < 2; ++k) dst[m][k] = *(const LAS bf16x8*)(lds + PG8_SA(b, h) + aoff + m * 2048 + k * 1024); } while (0)
; #define PG8_BAR __builtin_amdgcn_s_barrier()
; template <class Epi, class Sched>
; __device__ __forceinline__ void gemm_phase(LAS unsigned char* lds, const Gemm g, const Sched S, const Epi E, const int tid) {
;     ...
;             PG8_LDB(B0, 1, 0); PG8_LDB(B1, 1, 1); PG8_SCHED; PG8_LDA(At, 1, 0); PG8_STAGE(PG8_SA(0, 1), a2 + hstepA, voffA);
;             PG8_WAIT_V(8); PG8_WAIT_L(0); PG8_BAR; PG8_MMA(0, 0, At, B0); PG8_MMA(0, 1, At, B1); PG8_BAR; PG8_SCHED;
	s_add_i32 s21, 0, 0x18000
	v_add_u32_e32 v0, s21, v177
	s_add_i32 s22, 0, 0x1c000
	ds_read_b128 v[150:153], v0
	ds_read_b128 v[154:157], v0 offset:1024
	ds_read_b128 v[158:161], v0 offset:2048
	ds_read_b128 v[162:165], v0 offset:3072
	v_add_u32_e32 v0, s22, v177
	ds_read_b128 v[166:169], v0
	ds_read_b128 v[170:173], v0 offset:1024
	ds_read_b128 v[180:183], v0 offset:2048
	ds_read_b128 v[184:187], v0 offset:3072
	s_add_u32 s16, s16, 0x40000
	s_addc_u32 s17, s17, 0
	s_mov_b32 m0, s74
	v_lshl_add_u64 v[222:223], s[16:17], 0, v[130:131]
	ds_read_b128 v[188:191], v179 offset:32768
	ds_read_b128 v[206:209], v179 offset:33792
	ds_read_b128 v[218:221], v179 offset:34816
	ds_read_b128 v[232:235], v179 offset:35840
	ds_read_b128 v[236:239], v179 offset:36864
	ds_read_b128 v[240:243], v179 offset:37888
	ds_read_b128 v[244:247], v179 offset:38912
	ds_read_b128 v[248:251], v179 offset:39936
	global_load_lds_dwordx4 v[222:223], off
	v_lshl_add_u64 v[222:223], s[16:17], 0, v[134:135]
	s_mov_b32 m0, s75
	s_nop 0
	global_load_lds_dwordx4 v[222:223], off
	s_waitcnt vmcnt(8)
	s_waitcnt lgkmcnt(0)
	s_barrier
	s_setprio 1
	s_waitcnt lgkmcnt(0)
	v_mfma_f32_16x16x32_bf16 v[126:129], v[150:153], v[188:191], v[126:129]
	v_mfma_f32_16x16x32_bf16 v[122:125], v[158:161], v[188:191], v[122:125]
	v_mfma_f32_16x16x32_bf16 v[110:113], v[150:153], v[218:221], v[110:113]
	v_mfma_f32_16x16x32_bf16 v[106:109], v[158:161], v[218:221], v[106:109]
	v_mfma_f32_16x16x32_bf16 v[94:97], v[150:153], v[236:239], v[94:97]
	v_mfma_f32_16x16x32_bf16 v[90:93], v[158:161], v[236:239], v[90:93]
	v_mfma_f32_16x16x32_bf16 v[78:81], v[150:153], v[244:247], v[78:81]
	v_mfma_f32_16x16x32_bf16 v[74:77], v[158:161], v[244:247], v[74:77]
	v_mfma_f32_16x16x32_bf16 v[126:129], v[154:157], v[206:209], v[126:129]
	v_mfma_f32_16x16x32_bf16 v[122:125], v[162:165], v[206:209], v[122:125]
	v_mfma_f32_16x16x32_bf16 v[110:113], v[154:157], v[232:235], v[110:113]
	v_mfma_f32_16x16x32_bf16 v[106:109], v[162:165], v[232:235], v[106:109]
	v_mfma_f32_16x16x32_bf16 v[94:97], v[154:157], v[240:243], v[94:97]
	v_mfma_f32_16x16x32_bf16 v[90:93], v[162:165], v[240:243], v[90:93]
	v_mfma_f32_16x16x32_bf16 v[78:81], v[154:157], v[248:251], v[78:81]
	v_mfma_f32_16x16x32_bf16 v[74:77], v[162:165], v[248:251], v[74:77]
	s_setprio 0
	s_setprio 1
	v_mfma_f32_16x16x32_bf16 v[118:121], v[166:169], v[188:191], v[118:121]
	v_mfma_f32_16x16x32_bf16 v[114:117], v[180:183], v[188:191], v[114:117]
	v_mfma_f32_16x16x32_bf16 v[102:105], v[166:169], v[218:221], v[102:105]
	v_mfma_f32_16x16x32_bf16 v[98:101], v[180:183], v[218:221], v[98:101]
	v_mfma_f32_16x16x32_bf16 v[86:89], v[166:169], v[236:239], v[86:89]
	v_mfma_f32_16x16x32_bf16 v[82:85], v[180:183], v[236:239], v[82:85]
	v_mfma_f32_16x16x32_bf16 v[70:73], v[166:169], v[244:247], v[70:73]
	v_mfma_f32_16x16x32_bf16 v[66:69], v[180:183], v[244:247], v[66:69]
	v_mfma_f32_16x16x32_bf16 v[118:121], v[170:173], v[206:209], v[118:121]
	v_mfma_f32_16x16x32_bf16 v[114:117], v[184:187], v[206:209], v[114:117]
	v_mfma_f32_16x16x32_bf16 v[102:105], v[170:173], v[232:235], v[102:105]
	v_mfma_f32_16x16x32_bf16 v[98:101], v[184:187], v[232:235], v[98:101]
	v_mfma_f32_16x16x32_bf16 v[86:89], v[170:173], v[240:243], v[86:89]
	v_mfma_f32_16x16x32_bf16 v[82:85], v[184:187], v[240:243], v[82:85]
	v_mfma_f32_16x16x32_bf16 v[70:73], v[170:173], v[248:251], v[70:73]
	v_mfma_f32_16x16x32_bf16 v[66:69], v[184:187], v[248:251], v[66:69]
	s_setprio 0
	s_barrier
; #define PG8_STAGE(bufoff, gbase, voff) do { _Pragma("unroll") for (int _i = 0; _i < 2; ++_i) \
;         __builtin_amdgcn_global_load_lds((const unsigned*)((const char*)(gbase) + (voff)[_i]), (LAS unsigned*)(lds + (bufoff) + ldsw + _i * 8192), 16, 0, 0); } while (0)
; #define PG8_LDA(dst, b, h) do { _Pragma("unroll") for (int m = 0; m < 4; ++m) _Pragma("unroll") for (int k = 0; k < 2; ++k) dst[m][k] = *(const LAS bf16x8*)(lds + PG8_SA(b, h) + aoff + m * 2048 + k * 1024); } while (0)
; #define PG8_MMA(ai, bj, At, Bt) do { __builtin_amdgcn_s_setprio(1); _Pragma("unroll") for (int m = 0; m < 4; ++m) _Pragma("unroll") for (int n = 0; n < 2; ++n) _Pragma("unroll") for (int k = 0; k < 2; ++k) \
;         acc[ai][bj][m][n] = __builtin_amdgcn_mfma_f32_16x16x32_bf16(Bt[n][k], At[m][k], acc[ai][bj][m][n], 0, 0, 0); __builtin_amdgcn_s_setprio(0); } while (0)
; #define PG8_WAIT_V(n) asm volatile("s_waitcnt vmcnt(" #n ")" ::: "memory")
; #define PG8_WAIT_L(n) asm volatile("s_waitcnt lgkmcnt(" #n ")" ::: "memory")
; #define PG8_BAR __builtin_amdgcn_s_barrier()
; #define PG8_SCHED __builtin_amdgcn_sched_barrier(0)
; #define PG8_STAGE(bufoff, gbase, voff, q64) do { \
;         __builtin_amdgcn_global_load_lds((const unsigned*)((const char*)(gbase) + (voff)), (LAS unsigned*)(lds + (bufoff) + ldsw), 16, 0, 0); \
;         __builtin_amdgcn_global_load_lds((const unsigned*)((const char*)(gbase) + (q64) + (voff)), (LAS unsigned*)(lds + (bufoff) + ldsw + 8192), 16, 0, 0); } while (0)
; #define PG8_LDA(dst, b, h) do { _Pragma("unroll") for (int m = 0; m < 4; ++m) _Pragma("unroll") for (int k = 0; k < 2; ++k) dst[m][k] = *(const LAS bf16x8*)(lds + PG8_SA(b, h) + aoff + m * 2048 + k * 1024); } while (0)
; #define PG8_WAIT_V(n) asm volatile("s_waitcnt vmcnt(" #n ")" ::: "memory")
; #define PG8_WAIT_L(n) asm volatile("s_waitcnt lgkmcnt(" #n ")" ::: "memory")
; #define PG8_BAR __builtin_amdgcn_s_barrier()
; template <class Epi, class Sched>
; __device__ __forceinline__ void gemm_phase(LAS unsigned char* lds, const Gemm g, const Sched S, const Epi E, const int tid) {
;     ...
;             PG8_LDA(At, 1, 1); PG8_STAGE(PG8_SB(1, 0), b3, voffB); PG8_STAGE(PG8_SB(1, 1), b3 + hstepB, voffB); PG8_STAGE(PG8_SA(1, 0), a3, voffA);
;             PG8_WAIT_V(8); PG8_WAIT_L(0); PG8_BAR; PG8_MMA(1, 0, At, B0); PG8_MMA(1, 1, At, B1); PG8_BAR; PG8_SCHED;
;         }
	s_add_i32 s16, s21, s71
	v_lshl_add_u64 v[174:175], v[174:175], 0, s[0:1]
	s_mov_b32 m0, s16
	ds_read_b128 v[188:191], v179 offset:49152
	ds_read_b128 v[206:209], v179 offset:50176
	ds_read_b128 v[218:221], v179 offset:51200
	ds_read_b128 v[232:235], v179 offset:52224
	ds_read_b128 v[236:239], v179 offset:53248
	ds_read_b128 v[240:243], v179 offset:54272
	ds_read_b128 v[244:247], v179 offset:55296
	ds_read_b128 v[248:251], v179 offset:56320
	global_load_lds_dwordx4 v[174:175], off
	s_add_i32 m0, s16, 0x2000
	s_add_u32 s6, s6, 0x40080
	v_lshl_add_u64 v[174:175], v[192:193], 0, s[0:1]
	s_addc_u32 s7, s7, 0
	s_add_i32 s16, s22, s71
	global_load_lds_dwordx4 v[174:175], off
	v_lshl_add_u64 v[174:175], s[6:7], 0, v[132:133]
	s_mov_b32 m0, s16
	s_nop 0
	global_load_lds_dwordx4 v[174:175], off
	v_lshl_add_u64 v[174:175], s[6:7], 0, v[136:137]
	s_add_i32 m0, s16, 0x2000
	s_nop 0
	global_load_lds_dwordx4 v[174:175], off
	v_lshl_add_u64 v[174:175], v[194:195], 0, s[0:1]
	s_mov_b32 m0, s78
	s_nop 0
	global_load_lds_dwordx4 v[174:175], off
	v_lshl_add_u64 v[174:175], v[210:211], 0, s[0:1]
	s_mov_b32 m0, s79
	s_nop 0
	global_load_lds_dwordx4 v[174:175], off
	s_waitcnt vmcnt(8)
	s_waitcnt lgkmcnt(0)
	s_barrier
	s_setprio 1
	s_waitcnt lgkmcnt(0)
	v_mfma_f32_16x16x32_bf16 v[62:65], v[150:153], v[188:191], v[62:65]
	v_mfma_f32_16x16x32_bf16 v[58:61], v[158:161], v[188:191], v[58:61]
	v_mfma_f32_16x16x32_bf16 v[46:49], v[150:153], v[218:221], v[46:49]
	v_mfma_f32_16x16x32_bf16 v[42:45], v[158:161], v[218:221], v[42:45]
	v_mfma_f32_16x16x32_bf16 v[30:33], v[150:153], v[236:239], v[30:33]
	v_mfma_f32_16x16x32_bf16 v[26:29], v[158:161], v[236:239], v[26:29]
	v_mfma_f32_16x16x32_bf16 v[14:17], v[150:153], v[244:247], v[14:17]
	v_mfma_f32_16x16x32_bf16 v[10:13], v[158:161], v[244:247], v[10:13]
	v_mfma_f32_16x16x32_bf16 v[62:65], v[154:157], v[206:209], v[62:65]
	v_mfma_f32_16x16x32_bf16 v[58:61], v[162:165], v[206:209], v[58:61]
	v_mfma_f32_16x16x32_bf16 v[46:49], v[154:157], v[232:235], v[46:49]
	v_mfma_f32_16x16x32_bf16 v[42:45], v[162:165], v[232:235], v[42:45]
	v_mfma_f32_16x16x32_bf16 v[30:33], v[154:157], v[240:243], v[30:33]
	v_mfma_f32_16x16x32_bf16 v[26:29], v[162:165], v[240:243], v[26:29]
	v_mfma_f32_16x16x32_bf16 v[14:17], v[154:157], v[248:251], v[14:17]
	v_mfma_f32_16x16x32_bf16 v[10:13], v[162:165], v[248:251], v[10:13]
	s_setprio 0
	s_setprio 1
	v_mfma_f32_16x16x32_bf16 v[54:57], v[166:169], v[188:191], v[54:57]
	v_mfma_f32_16x16x32_bf16 v[50:53], v[180:183], v[188:191], v[50:53]
	v_mfma_f32_16x16x32_bf16 v[38:41], v[166:169], v[218:221], v[38:41]
	v_mfma_f32_16x16x32_bf16 v[34:37], v[180:183], v[218:221], v[34:37]
	v_mfma_f32_16x16x32_bf16 v[22:25], v[166:169], v[236:239], v[22:25]
	v_mfma_f32_16x16x32_bf16 v[18:21], v[180:183], v[236:239], v[18:21]
	v_mfma_f32_16x16x32_bf16 v[6:9], v[166:169], v[244:247], v[6:9]
	v_mfma_f32_16x16x32_bf16 v[2:5], v[180:183], v[244:247], v[2:5]
	v_mfma_f32_16x16x32_bf16 v[54:57], v[170:173], v[206:209], v[54:57]
	v_mfma_f32_16x16x32_bf16 v[50:53], v[184:187], v[206:209], v[50:53]
	v_mfma_f32_16x16x32_bf16 v[38:41], v[170:173], v[232:235], v[38:41]
	v_mfma_f32_16x16x32_bf16 v[34:37], v[184:187], v[232:235], v[34:37]
	v_mfma_f32_16x16x32_bf16 v[22:25], v[170:173], v[240:243], v[22:25]
	v_mfma_f32_16x16x32_bf16 v[18:21], v[184:187], v[240:243], v[18:21]
	v_mfma_f32_16x16x32_bf16 v[6:9], v[170:173], v[248:251], v[6:9]
	v_mfma_f32_16x16x32_bf16 v[2:5], v[184:187], v[248:251], v[2:5]
	s_setprio 0
	s_barrier
	s_add_u32 s18, s18, 0x100
	s_addc_u32 s19, s19, 0
	s_add_u32 s4, s4, 0x100
	s_addc_u32 s5, s5, 0
	s_cmp_ge_i32 s20, s77
	s_mov_b32 s6, s20
	s_cbranch_scc0 .LBB0_548

; #define PG8_STAGE(bufoff, gbase, voff) do { _Pragma("unroll") for (int _i = 0; _i < 2; ++_i) \
;         __builtin_amdgcn_global_load_lds((const unsigned*)((const char*)(gbase) + (voff)[_i]), (LAS unsigned*)(lds + (bufoff) + ldsw + _i * 8192), 16, 0, 0); } while (0)
; #define PG8_LDA(dst, b, h) do { _Pragma("unroll") for (int m = 0; m < 4; ++m) _Pragma("unroll") for (int k = 0; k < 2; ++k) dst[m][k] = *(const LAS bf16x8*)(lds + PG8_SA(b, h) + aoff + m * 2048 + k * 1024); } while (0)
; #define PG8_LDB(dst, b, h) do { _Pragma("unroll") for (int n = 0; n < 2; ++n) _Pragma("unroll") for (int k = 0; k < 2; ++k) dst[n][k] = *(const LAS bf16x8*)(lds + PG8_SB(b, h) + boff + n * 2048 + k * 1024); } while (0)
; #define PG8_SCHED __builtin_amdgcn_sched_barrier(0)
; #define PG8_STAGE(bufoff, gbase, voff, q64) do { \
;         __builtin_amdgcn_global_load_lds((const unsigned*)((const char*)(gbase) + (voff)), (LAS unsigned*)(lds + (bufoff) + ldsw), 16, 0, 0); \
;         __builtin_amdgcn_global_load_lds((const unsigned*)((const char*)(gbase) + (q64) + (voff)), (LAS unsigned*)(lds + (bufoff) + ldsw + 8192), 16, 0, 0); } while (0)
; #define PG8_SCHED __builtin_amdgcn_sched_barrier(0)
; template <class Epi, class Sched>
; __device__ __forceinline__ void gemm_phase(LAS unsigned char* lds, const Gemm g, const Sched S, const Epi E, const int tid) {
;     ...
;         const bool has_next = S.next(ui + 1, nxt);
;         const char* nA = has_next ? (const char*)g.A + (size_t)nxt.pm * tstepA : cA; const char* nB = has_next ? (const char*)g.Bt + (size_t)nxt.pn * tstepB : cB;
;         for (int t = 0; t < nt; t += 2) {
;             const bool last = (t == nt - 2);
;             const char* a1 = cA + (size_t)(t + 1) * kstep;
;             const char* a2 = last ? nA : cA + (size_t)(t + 2) * kstep; const char* b2 = last ? nB : cB + (size_t)(t + 2) * kstep;
;             const char* a3 = a2 + kstep; const char* b3 = b2 + kstep;
;             PG8_LDB(B0, 0, 0); PG8_LDB(B1, 0, 1); PG8_SCHED; PG8_LDA(At, 0, 0); PG8_STAGE(PG8_SA(1, 1), a1 + hstepA, voffA);
;     ...
; #pragma unroll
;         for (int a = 0; a < 2; ++a)
; #pragma unroll
;             for (int b = 0; b < 2; ++b)
; #pragma unroll
;                 for (int m = 0; m < 4; ++m)
; #pragma unroll
;                     for (int n = 0; n < 2; ++n) acc[a][b][m][n] = (f32x4){0.f, 0.f, 0.f, 0.f};
;         cur = nxt; cA = nA; cB = nB; ++ui;
.LBB0_1098:
	v_mov_b32_e32 v125, 0
	s_andn2_b64 vcc, exec, s[42:43]
	v_mov_b32_e32 v124, v125
	v_mov_b32_e32 v123, v125
	v_mov_b32_e32 v122, v125
	v_mov_b32_e32 v129, v125
	v_mov_b32_e32 v128, v125
	v_mov_b32_e32 v127, v125
	v_mov_b32_e32 v126, v125
	v_mov_b32_e32 v113, v125
	v_mov_b32_e32 v112, v125
	v_mov_b32_e32 v111, v125
	v_mov_b32_e32 v110, v125
	v_mov_b32_e32 v109, v125
	v_mov_b32_e32 v108, v125
	v_mov_b32_e32 v107, v125
	v_mov_b32_e32 v106, v125
	v_mov_b32_e32 v97, v125
	v_mov_b32_e32 v96, v125
	v_mov_b32_e32 v95, v125
	v_mov_b32_e32 v94, v125
	v_mov_b32_e32 v93, v125
	v_mov_b32_e32 v92, v125
	v_mov_b32_e32 v91, v125
	v_mov_b32_e32 v90, v125
	v_mov_b32_e32 v81, v125
	v_mov_b32_e32 v80, v125
	v_mov_b32_e32 v79, v125
	v_mov_b32_e32 v78, v125
	v_mov_b32_e32 v77, v125
	v_mov_b32_e32 v76, v125
	v_mov_b32_e32 v75, v125
	v_mov_b32_e32 v74, v125
	v_mov_b32_e32 v121, v125
	v_mov_b32_e32 v120, v125
	v_mov_b32_e32 v119, v125
	v_mov_b32_e32 v118, v125
	v_mov_b32_e32 v117, v125
	v_mov_b32_e32 v116, v125
	v_mov_b32_e32 v115, v125
	v_mov_b32_e32 v114, v125
	v_mov_b32_e32 v105, v125
	v_mov_b32_e32 v104, v125
	v_mov_b32_e32 v103, v125
	v_mov_b32_e32 v102, v125
	v_mov_b32_e32 v101, v125
	v_mov_b32_e32 v100, v125
	v_mov_b32_e32 v99, v125
	v_mov_b32_e32 v98, v125
	v_mov_b32_e32 v89, v125
	v_mov_b32_e32 v88, v125
	v_mov_b32_e32 v87, v125
	v_mov_b32_e32 v86, v125
	v_mov_b32_e32 v85, v125
	v_mov_b32_e32 v84, v125
	v_mov_b32_e32 v83, v125
	v_mov_b32_e32 v82, v125
	v_mov_b32_e32 v73, v125
	v_mov_b32_e32 v72, v125
	v_mov_b32_e32 v71, v125
	v_mov_b32_e32 v70, v125
	v_mov_b32_e32 v69, v125
	v_mov_b32_e32 v68, v125
	v_mov_b32_e32 v67, v125
	v_mov_b32_e32 v66, v125
	v_mov_b32_e32 v65, v125
	v_mov_b32_e32 v64, v125
	v_mov_b32_e32 v63, v125
	v_mov_b32_e32 v62, v125
	v_mov_b32_e32 v61, v125
	v_mov_b32_e32 v60, v125
	v_mov_b32_e32 v59, v125
	v_mov_b32_e32 v58, v125
	v_mov_b32_e32 v49, v125
	v_mov_b32_e32 v48, v125
	v_mov_b32_e32 v47, v125
	v_mov_b32_e32 v46, v125
	v_mov_b32_e32 v45, v125
	v_mov_b32_e32 v44, v125
	v_mov_b32_e32 v43, v125
	v_mov_b32_e32 v42, v125
	v_mov_b32_e32 v33, v125
	v_mov_b32_e32 v32, v125
	v_mov_b32_e32 v31, v125
	v_mov_b32_e32 v30, v125
	v_mov_b32_e32 v29, v125
	v_mov_b32_e32 v28, v125
	v_mov_b32_e32 v27, v125
	v_mov_b32_e32 v26, v125
	v_mov_b32_e32 v17, v125
	v_mov_b32_e32 v16, v125
	v_mov_b32_e32 v15, v125
	v_mov_b32_e32 v14, v125
	v_mov_b32_e32 v13, v125
	v_mov_b32_e32 v12, v125
	v_mov_b32_e32 v11, v125
	v_mov_b32_e32 v10, v125
	v_mov_b32_e32 v57, v125
	v_mov_b32_e32 v56, v125
	v_mov_b32_e32 v55, v125
	v_mov_b32_e32 v54, v125
	v_mov_b32_e32 v53, v125
	v_mov_b32_e32 v52, v125
	v_mov_b32_e32 v51, v125
	v_mov_b32_e32 v50, v125
	v_mov_b32_e32 v41, v125
	v_mov_b32_e32 v40, v125
	v_mov_b32_e32 v39, v125
	v_mov_b32_e32 v38, v125
	v_mov_b32_e32 v37, v125
	v_mov_b32_e32 v36, v125
	v_mov_b32_e32 v35, v125
	v_mov_b32_e32 v34, v125
	v_mov_b32_e32 v25, v125
	v_mov_b32_e32 v24, v125
	v_mov_b32_e32 v23, v125
	v_mov_b32_e32 v22, v125
	v_mov_b32_e32 v21, v125
	v_mov_b32_e32 v20, v125
	v_mov_b32_e32 v19, v125
	v_mov_b32_e32 v18, v125
	v_mov_b32_e32 v9, v125
	v_mov_b32_e32 v8, v125
	v_mov_b32_e32 v7, v125
	v_mov_b32_e32 v6, v125
	v_mov_b32_e32 v5, v125
	v_mov_b32_e32 v4, v125
	v_mov_b32_e32 v3, v125
	s_waitcnt lgkmcnt(0)
	v_mov_b32_e32 v2, v125
	s_cbranch_vccnz .LBB0_1102
	s_add_u32 s38, s24, 0x100
	s_addc_u32 s39, s25, 0
	s_add_u32 s24, s28, 0x80
	v_mov_b32_e32 v2, 0
	s_addc_u32 s25, s29, 0
	s_mov_b32 s28, 0
.LBB0_1100:
	s_add_i32 s40, s28, 2
	s_add_u32 s41, s24, 0x80
	s_addc_u32 s29, s25, 0
	s_add_i32 s50, 0, 0x10000
	s_cmp_eq_u32 s56, s28
	s_cselect_b32 s29, s9, s29
	s_cselect_b32 s28, s8, s41
	v_add_u32_e32 v0, s50, v152
	s_cselect_b32 s49, s47, s39
	s_cselect_b32 s48, s46, s38
	s_add_i32 s41, 0, 0x14000
	ds_read_b128 v[148:151], v0
	ds_read_b128 v[154:157], v0 offset:1024
	ds_read_b128 v[158:161], v0 offset:2048
	ds_read_b128 v[162:165], v0 offset:3072
	v_add_u32_e32 v0, s41, v152
	ds_read_b128 v[166:169], v0
	ds_read_b128 v[170:173], v0 offset:1024
	ds_read_b128 v[174:177], v0 offset:2048
	ds_read_b128 v[178:181], v0 offset:3072
	v_lshl_add_u64 v[190:191], s[24:25], 0, v[146:147]
	s_add_i32 m0, s18, 0xc000
	ds_read_b128 v[182:185], v153
	ds_read_b128 v[186:189], v153 offset:1024
	ds_read_b128 v[206:209], v153 offset:2048
	ds_read_b128 v[232:235], v153 offset:3072
	ds_read_b128 v[236:239], v153 offset:4096
	ds_read_b128 v[240:243], v153 offset:5120
	ds_read_b128 v[244:247], v153 offset:6144
	ds_read_b128 v[248:251], v153 offset:7168
	global_load_lds_dwordx4 v[190:191], off
	v_lshl_add_u64 v[190:191], s[24:25], 0, v[144:145]
	s_add_i32 m0, s18, 0xe000
	s_nop 0
	global_load_lds_dwordx4 v[190:191], off
	s_waitcnt vmcnt(8)
	s_waitcnt lgkmcnt(0)
	s_barrier
; #define PG8_STAGE(bufoff, gbase, voff) do { _Pragma("unroll") for (int _i = 0; _i < 2; ++_i) \
;         __builtin_amdgcn_global_load_lds((const unsigned*)((const char*)(gbase) + (voff)[_i]), (LAS unsigned*)(lds + (bufoff) + ldsw + _i * 8192), 16, 0, 0); } while (0)
; #define PG8_LDA(dst, b, h) do { _Pragma("unroll") for (int m = 0; m < 4; ++m) _Pragma("unroll") for (int k = 0; k < 2; ++k) dst[m][k] = *(const LAS bf16x8*)(lds + PG8_SA(b, h) + aoff + m * 2048 + k * 1024); } while (0)
; #define PG8_MMA(ai, bj, At, Bt) do { __builtin_amdgcn_s_setprio(1); _Pragma("unroll") for (int m = 0; m < 4; ++m) _Pragma("unroll") for (int n = 0; n < 2; ++n) _Pragma("unroll") for (int k = 0; k < 2; ++k) \
;         acc[ai][bj][m][n] = __builtin_amdgcn_mfma_f32_16x16x32_bf16(Bt[n][k], At[m][k], acc[ai][bj][m][n], 0, 0, 0); __builtin_amdgcn_s_setprio(0); } while (0)
; #define PG8_WAIT_V(n) asm volatile("s_waitcnt vmcnt(" #n ")" ::: "memory")
; #define PG8_WAIT_L(n) asm volatile("s_waitcnt lgkmcnt(" #n ")" ::: "memory")
; #define PG8_BAR __builtin_amdgcn_s_barrier()
; #define PG8_SCHED __builtin_amdgcn_sched_barrier(0)
; #define PG8_STAGE(bufoff, gbase, voff, q64) do { \
;         __builtin_amdgcn_global_load_lds((const unsigned*)((const char*)(gbase) + (voff)), (LAS unsigned*)(lds + (bufoff) + ldsw), 16, 0, 0); \
;         __builtin_amdgcn_global_load_lds((const unsigned*)((const char*)(gbase) + (q64) + (voff)), (LAS unsigned*)(lds + (bufoff) + ldsw + 8192), 16, 0, 0); } while (0)
; #define PG8_LDA(dst, b, h) do { _Pragma("unroll") for (int m = 0; m < 4; ++m) _Pragma("unroll") for (int k = 0; k < 2; ++k) dst[m][k] = *(const LAS bf16x8*)(lds + PG8_SA(b, h) + aoff + m * 2048 + k * 1024); } while (0)
; #define PG8_WAIT_V(n) asm volatile("s_waitcnt vmcnt(" #n ")" ::: "memory")
; #define PG8_BAR __builtin_amdgcn_s_barrier()
; template <class Epi, class Sched>
; __device__ __forceinline__ void gemm_phase(LAS unsigned char* lds, const Gemm g, const Sched S, const Epi E, const int tid) {
;     ...
;             PG8_WAIT_V(8); PG8_WAIT_L(0); PG8_BAR; PG8_MMA(0, 0, At, B0); PG8_MMA(0, 1, At, B1); PG8_BAR; PG8_SCHED;
;             PG8_LDA(At, 0, 1); PG8_STAGE(PG8_SB(0, 0), b2, voffB); PG8_STAGE(PG8_SB(0, 1), b2 + hstepB, voffB); PG8_STAGE(PG8_SA(0, 0), a2, voffA);
;             PG8_WAIT_V(8); PG8_WAIT_L(0); PG8_BAR; PG8_MMA(1, 0, At, B0); PG8_MMA(1, 1, At, B1); PG8_BAR; PG8_SCHED;
	s_setprio 1
	s_waitcnt lgkmcnt(0)
	v_mfma_f32_16x16x32_bf16 v[122:125], v[148:151], v[182:185], v[122:125]
	v_mfma_f32_16x16x32_bf16 v[126:129], v[158:161], v[182:185], v[126:129]
	v_mfma_f32_16x16x32_bf16 v[110:113], v[148:151], v[206:209], v[110:113]
	v_mfma_f32_16x16x32_bf16 v[106:109], v[158:161], v[206:209], v[106:109]
	v_mfma_f32_16x16x32_bf16 v[94:97], v[148:151], v[236:239], v[94:97]
	v_mfma_f32_16x16x32_bf16 v[90:93], v[158:161], v[236:239], v[90:93]
	v_mfma_f32_16x16x32_bf16 v[78:81], v[148:151], v[244:247], v[78:81]
	v_mfma_f32_16x16x32_bf16 v[74:77], v[158:161], v[244:247], v[74:77]
	v_mfma_f32_16x16x32_bf16 v[122:125], v[154:157], v[186:189], v[122:125]
	v_mfma_f32_16x16x32_bf16 v[126:129], v[162:165], v[186:189], v[126:129]
	v_mfma_f32_16x16x32_bf16 v[110:113], v[154:157], v[232:235], v[110:113]
	v_mfma_f32_16x16x32_bf16 v[106:109], v[162:165], v[232:235], v[106:109]
	v_mfma_f32_16x16x32_bf16 v[94:97], v[154:157], v[240:243], v[94:97]
	v_mfma_f32_16x16x32_bf16 v[90:93], v[162:165], v[240:243], v[90:93]
	v_mfma_f32_16x16x32_bf16 v[78:81], v[154:157], v[248:251], v[78:81]
	v_mfma_f32_16x16x32_bf16 v[74:77], v[162:165], v[248:251], v[74:77]
	s_setprio 0
	s_setprio 1
	v_mfma_f32_16x16x32_bf16 v[118:121], v[166:169], v[182:185], v[118:121]
	v_mfma_f32_16x16x32_bf16 v[114:117], v[174:177], v[182:185], v[114:117]
	v_mfma_f32_16x16x32_bf16 v[102:105], v[166:169], v[206:209], v[102:105]
	v_mfma_f32_16x16x32_bf16 v[98:101], v[174:177], v[206:209], v[98:101]
	v_mfma_f32_16x16x32_bf16 v[86:89], v[166:169], v[236:239], v[86:89]
	v_mfma_f32_16x16x32_bf16 v[82:85], v[174:177], v[236:239], v[82:85]
	v_mfma_f32_16x16x32_bf16 v[70:73], v[166:169], v[244:247], v[70:73]
	v_mfma_f32_16x16x32_bf16 v[66:69], v[174:177], v[244:247], v[66:69]
	v_mfma_f32_16x16x32_bf16 v[118:121], v[170:173], v[186:189], v[118:121]
	v_mfma_f32_16x16x32_bf16 v[114:117], v[178:181], v[186:189], v[114:117]
	v_mfma_f32_16x16x32_bf16 v[102:105], v[170:173], v[232:235], v[102:105]
	v_mfma_f32_16x16x32_bf16 v[98:101], v[178:181], v[232:235], v[98:101]
	v_mfma_f32_16x16x32_bf16 v[86:89], v[170:173], v[240:243], v[86:89]
	v_mfma_f32_16x16x32_bf16 v[82:85], v[178:181], v[240:243], v[82:85]
	v_mfma_f32_16x16x32_bf16 v[70:73], v[170:173], v[248:251], v[70:73]
	v_mfma_f32_16x16x32_bf16 v[66:69], v[178:181], v[248:251], v[66:69]
	s_setprio 0
	s_barrier
	s_add_i32 s50, s50, s15
	v_lshl_add_u64 v[190:191], s[48:49], 0, v[136:137]
	s_mov_b32 m0, s50
	ds_read_b128 v[182:185], v153 offset:16384
	ds_read_b128 v[186:189], v153 offset:17408
	ds_read_b128 v[206:209], v153 offset:18432
	ds_read_b128 v[232:235], v153 offset:19456
	ds_read_b128 v[236:239], v153 offset:20480
	ds_read_b128 v[240:243], v153 offset:21504
	ds_read_b128 v[244:247], v153 offset:22528
	ds_read_b128 v[248:251], v153 offset:23552
	global_load_lds_dwordx4 v[190:191], off
	s_add_i32 m0, s50, 0x2000
	v_lshl_add_u64 v[210:211], s[48:49], 0, v[132:133]
	s_add_u32 s48, s48, s22
	s_addc_u32 s49, s49, s23
	s_add_i32 s41, s41, s15
	global_load_lds_dwordx4 v[210:211], off
	v_lshl_add_u64 v[218:219], s[48:49], 0, v[136:137]
	s_mov_b32 m0, s41
	v_lshl_add_u64 v[220:221], s[48:49], 0, v[132:133]
	global_load_lds_dwordx4 v[218:219], off
	s_add_i32 m0, s41, 0x2000
	v_lshl_add_u64 v[192:193], s[28:29], 0, v[138:139]
	global_load_lds_dwordx4 v[220:221], off
	s_mov_b32 m0, s18
	v_lshl_add_u64 v[222:223], s[28:29], 0, v[134:135]
	global_load_lds_dwordx4 v[192:193], off
	s_mov_b32 m0, s19
	s_nop 0
	global_load_lds_dwordx4 v[222:223], off
	s_waitcnt vmcnt(8)
	s_waitcnt lgkmcnt(0)
	s_barrier
	s_setprio 1
	s_waitcnt lgkmcnt(0)
	v_mfma_f32_16x16x32_bf16 v[62:65], v[148:151], v[182:185], v[62:65]
	v_mfma_f32_16x16x32_bf16 v[58:61], v[158:161], v[182:185], v[58:61]
	v_mfma_f32_16x16x32_bf16 v[46:49], v[148:151], v[206:209], v[46:49]
	v_mfma_f32_16x16x32_bf16 v[42:45], v[158:161], v[206:209], v[42:45]
	v_mfma_f32_16x16x32_bf16 v[30:33], v[148:151], v[236:239], v[30:33]
	v_mfma_f32_16x16x32_bf16 v[26:29], v[158:161], v[236:239], v[26:29]
	v_mfma_f32_16x16x32_bf16 v[14:17], v[148:151], v[244:247], v[14:17]
	v_mfma_f32_16x16x32_bf16 v[10:13], v[158:161], v[244:247], v[10:13]
	v_mfma_f32_16x16x32_bf16 v[62:65], v[154:157], v[186:189], v[62:65]
	v_mfma_f32_16x16x32_bf16 v[58:61], v[162:165], v[186:189], v[58:61]
	v_mfma_f32_16x16x32_bf16 v[46:49], v[154:157], v[232:235], v[46:49]
	v_mfma_f32_16x16x32_bf16 v[42:45], v[162:165], v[232:235], v[42:45]
	v_mfma_f32_16x16x32_bf16 v[30:33], v[154:157], v[240:243], v[30:33]
	v_mfma_f32_16x16x32_bf16 v[26:29], v[162:165], v[240:243], v[26:29]
	v_mfma_f32_16x16x32_bf16 v[14:17], v[154:157], v[248:251], v[14:17]
	v_mfma_f32_16x16x32_bf16 v[10:13], v[162:165], v[248:251], v[10:13]
	s_setprio 0
	s_setprio 1
	v_mfma_f32_16x16x32_bf16 v[54:57], v[166:169], v[182:185], v[54:57]
	v_mfma_f32_16x16x32_bf16 v[50:53], v[174:177], v[182:185], v[50:53]
	v_mfma_f32_16x16x32_bf16 v[38:41], v[166:169], v[206:209], v[38:41]
	v_mfma_f32_16x16x32_bf16 v[34:37], v[174:177], v[206:209], v[34:37]
	v_mfma_f32_16x16x32_bf16 v[22:25], v[166:169], v[236:239], v[22:25]
	v_mfma_f32_16x16x32_bf16 v[18:21], v[174:177], v[236:239], v[18:21]
	v_mfma_f32_16x16x32_bf16 v[6:9], v[166:169], v[244:247], v[6:9]
	v_mfma_f32_16x16x32_bf16 v[2:5], v[174:177], v[244:247], v[2:5]
	v_mfma_f32_16x16x32_bf16 v[54:57], v[170:173], v[186:189], v[54:57]
	v_mfma_f32_16x16x32_bf16 v[50:53], v[178:181], v[186:189], v[50:53]
	v_mfma_f32_16x16x32_bf16 v[38:41], v[170:173], v[232:235], v[38:41]
	v_mfma_f32_16x16x32_bf16 v[34:37], v[178:181], v[232:235], v[34:37]
	v_mfma_f32_16x16x32_bf16 v[22:25], v[170:173], v[240:243], v[22:25]
	v_mfma_f32_16x16x32_bf16 v[18:21], v[178:181], v[240:243], v[18:21]
	v_mfma_f32_16x16x32_bf16 v[6:9], v[170:173], v[248:251], v[6:9]
	v_mfma_f32_16x16x32_bf16 v[2:5], v[178:181], v[248:251], v[2:5]
	s_setprio 0
	s_barrier
; #define PG8_STAGE(bufoff, gbase, voff) do { _Pragma("unroll") for (int _i = 0; _i < 2; ++_i) \
;         __builtin_amdgcn_global_load_lds((const unsigned*)((const char*)(gbase) + (voff)[_i]), (LAS unsigned*)(lds + (bufoff) + ldsw + _i * 8192), 16, 0, 0); } while (0)
; #define PG8_LDA(dst, b, h) do { _Pragma("unroll") for (int m = 0; m < 4; ++m) _Pragma("unroll") for (int k = 0; k < 2; ++k) dst[m][k] = *(const LAS bf16x8*)(lds + PG8_SA(b, h) + aoff + m * 2048 + k * 1024); } while (0)
; #define PG8_LDB(dst, b, h) do { _Pragma("unroll") for (int n = 0; n < 2; ++n) _Pragma("unroll") for (int k = 0; k < 2; ++k) dst[n][k] = *(const LAS bf16x8*)(lds + PG8_SB(b, h) + boff + n * 2048 + k * 1024); } while (0)
; #define PG8_MMA(ai, bj, At, Bt) do { __builtin_amdgcn_s_setprio(1); _Pragma("unroll") for (int m = 0; m < 4; ++m) _Pragma("unroll") for (int n = 0; n < 2; ++n) _Pragma("unroll") for (int k = 0; k < 2; ++k) \
;         acc[ai][bj][m][n] = __builtin_amdgcn_mfma_f32_16x16x32_bf16(Bt[n][k], At[m][k], acc[ai][bj][m][n], 0, 0, 0); __builtin_amdgcn_s_setprio(0); } while (0)
; #define PG8_WAIT_V(n) asm volatile("s_waitcnt vmcnt(" #n ")" ::: "memory")
; #define PG8_WAIT_L(n) asm volatile("s_waitcnt lgkmcnt(" #n ")" ::: "memory")
; #define PG8_BAR __builtin_amdgcn_s_barrier()
; #define PG8_SCHED __builtin_amdgcn_sched_barrier(0)
; #define PG8_STAGE(bufoff, gbase, voff, q64) do { \
;         __builtin_amdgcn_global_load_lds((const unsigned*)((const char*)(gbase) + (voff)), (LAS unsigned*)(lds + (bufoff) + ldsw), 16, 0, 0); \
;         __builtin_amdgcn_global_load_lds((const unsigned*)((const char*)(gbase) + (q64) + (voff)), (LAS unsigned*)(lds + (bufoff) + ldsw + 8192), 16, 0, 0); } while (0)
; #define PG8_LDA(dst, b, h) do { _Pragma("unroll") for (int m = 0; m < 4; ++m) _Pragma("unroll") for (int k = 0; k < 2; ++k) dst[m][k] = *(const LAS bf16x8*)(lds + PG8_SA(b, h) + aoff + m * 2048 + k * 1024); } while (0)
; #define PG8_BAR __builtin_amdgcn_s_barrier()
; template <class Epi, class Sched>
; __device__ __forceinline__ void gemm_phase(LAS unsigned char* lds, const Gemm g, const Sched S, const Epi E, const int tid) {
;     ...
;             PG8_LDB(B0, 1, 0); PG8_LDB(B1, 1, 1); PG8_SCHED; PG8_LDA(At, 1, 0); PG8_STAGE(PG8_SA(0, 1), a2 + hstepA, voffA);
;             PG8_WAIT_V(8); PG8_WAIT_L(0); PG8_BAR; PG8_MMA(0, 0, At, B0); PG8_MMA(0, 1, At, B1); PG8_BAR; PG8_SCHED;
	s_add_i32 s41, 0, 0x18000
	v_add_u32_e32 v0, s41, v152
	s_add_i32 s48, 0, 0x1c000
	ds_read_b128 v[148:151], v0
	ds_read_b128 v[154:157], v0 offset:1024
	ds_read_b128 v[158:161], v0 offset:2048
	ds_read_b128 v[162:165], v0 offset:3072
	v_add_u32_e32 v0, s48, v152
	ds_read_b128 v[166:169], v0
	ds_read_b128 v[170:173], v0 offset:1024
	ds_read_b128 v[174:177], v0 offset:2048
	ds_read_b128 v[178:181], v0 offset:3072
	s_add_u32 s28, s28, s22
	s_addc_u32 s29, s29, s23
	s_mov_b32 m0, s31
	v_lshl_add_u64 v[194:195], s[28:29], 0, v[138:139]
	ds_read_b128 v[182:185], v153 offset:32768
	ds_read_b128 v[186:189], v153 offset:33792
	ds_read_b128 v[206:209], v153 offset:34816
	ds_read_b128 v[232:235], v153 offset:35840
	ds_read_b128 v[236:239], v153 offset:36864
	ds_read_b128 v[240:243], v153 offset:37888
	ds_read_b128 v[244:247], v153 offset:38912
	ds_read_b128 v[248:251], v153 offset:39936
	global_load_lds_dwordx4 v[194:195], off
	v_lshl_add_u64 v[194:195], s[28:29], 0, v[134:135]
	s_mov_b32 m0, s34
	s_nop 0
	global_load_lds_dwordx4 v[194:195], off
	s_waitcnt vmcnt(8)
	s_waitcnt lgkmcnt(0)
	s_barrier
	s_setprio 1
	s_waitcnt lgkmcnt(0)
	v_mfma_f32_16x16x32_bf16 v[122:125], v[148:151], v[182:185], v[122:125]
	v_mfma_f32_16x16x32_bf16 v[126:129], v[158:161], v[182:185], v[126:129]
	v_mfma_f32_16x16x32_bf16 v[110:113], v[148:151], v[206:209], v[110:113]
	v_mfma_f32_16x16x32_bf16 v[106:109], v[158:161], v[206:209], v[106:109]
	v_mfma_f32_16x16x32_bf16 v[94:97], v[148:151], v[236:239], v[94:97]
	v_mfma_f32_16x16x32_bf16 v[90:93], v[158:161], v[236:239], v[90:93]
	v_mfma_f32_16x16x32_bf16 v[78:81], v[148:151], v[244:247], v[78:81]
	v_mfma_f32_16x16x32_bf16 v[74:77], v[158:161], v[244:247], v[74:77]
	v_mfma_f32_16x16x32_bf16 v[122:125], v[154:157], v[186:189], v[122:125]
	v_mfma_f32_16x16x32_bf16 v[126:129], v[162:165], v[186:189], v[126:129]
	v_mfma_f32_16x16x32_bf16 v[110:113], v[154:157], v[232:235], v[110:113]
	v_mfma_f32_16x16x32_bf16 v[106:109], v[162:165], v[232:235], v[106:109]
	v_mfma_f32_16x16x32_bf16 v[94:97], v[154:157], v[240:243], v[94:97]
	v_mfma_f32_16x16x32_bf16 v[90:93], v[162:165], v[240:243], v[90:93]
	v_mfma_f32_16x16x32_bf16 v[78:81], v[154:157], v[248:251], v[78:81]
	v_mfma_f32_16x16x32_bf16 v[74:77], v[162:165], v[248:251], v[74:77]
	s_setprio 0
	s_setprio 1
	v_mfma_f32_16x16x32_bf16 v[118:121], v[166:169], v[182:185], v[118:121]
	v_mfma_f32_16x16x32_bf16 v[114:117], v[174:177], v[182:185], v[114:117]
	v_mfma_f32_16x16x32_bf16 v[102:105], v[166:169], v[206:209], v[102:105]
	v_mfma_f32_16x16x32_bf16 v[98:101], v[174:177], v[206:209], v[98:101]
	v_mfma_f32_16x16x32_bf16 v[86:89], v[166:169], v[236:239], v[86:89]
	v_mfma_f32_16x16x32_bf16 v[82:85], v[174:177], v[236:239], v[82:85]
	v_mfma_f32_16x16x32_bf16 v[70:73], v[166:169], v[244:247], v[70:73]
	v_mfma_f32_16x16x32_bf16 v[66:69], v[174:177], v[244:247], v[66:69]
	v_mfma_f32_16x16x32_bf16 v[118:121], v[170:173], v[186:189], v[118:121]
	v_mfma_f32_16x16x32_bf16 v[114:117], v[178:181], v[186:189], v[114:117]
	v_mfma_f32_16x16x32_bf16 v[102:105], v[170:173], v[232:235], v[102:105]
	v_mfma_f32_16x16x32_bf16 v[98:101], v[178:181], v[232:235], v[98:101]
	v_mfma_f32_16x16x32_bf16 v[86:89], v[170:173], v[240:243], v[86:89]
	v_mfma_f32_16x16x32_bf16 v[82:85], v[178:181], v[240:243], v[82:85]
	v_mfma_f32_16x16x32_bf16 v[70:73], v[170:173], v[248:251], v[70:73]
	v_mfma_f32_16x16x32_bf16 v[66:69], v[178:181], v[248:251], v[66:69]
	s_setprio 0
	s_barrier
; #define PG8_STAGE(bufoff, gbase, voff) do { _Pragma("unroll") for (int _i = 0; _i < 2; ++_i) \
;         __builtin_amdgcn_global_load_lds((const unsigned*)((const char*)(gbase) + (voff)[_i]), (LAS unsigned*)(lds + (bufoff) + ldsw + _i * 8192), 16, 0, 0); } while (0)
; #define PG8_LDA(dst, b, h) do { _Pragma("unroll") for (int m = 0; m < 4; ++m) _Pragma("unroll") for (int k = 0; k < 2; ++k) dst[m][k] = *(const LAS bf16x8*)(lds + PG8_SA(b, h) + aoff + m * 2048 + k * 1024); } while (0)
; #define PG8_MMA(ai, bj, At, Bt) do { __builtin_amdgcn_s_setprio(1); _Pragma("unroll") for (int m = 0; m < 4; ++m) _Pragma("unroll") for (int n = 0; n < 2; ++n) _Pragma("unroll") for (int k = 0; k < 2; ++k) \
;         acc[ai][bj][m][n] = __builtin_amdgcn_mfma_f32_16x16x32_bf16(Bt[n][k], At[m][k], acc[ai][bj][m][n], 0, 0, 0); __builtin_amdgcn_s_setprio(0); } while (0)
; #define PG8_WAIT_V(n) asm volatile("s_waitcnt vmcnt(" #n ")" ::: "memory")
; #define PG8_WAIT_L(n) asm volatile("s_waitcnt lgkmcnt(" #n ")" ::: "memory")
; #define PG8_BAR __builtin_amdgcn_s_barrier()
; #define PG8_SCHED __builtin_amdgcn_sched_barrier(0)
; #define PG8_STAGE(bufoff, gbase, voff, q64) do { \
;         __builtin_amdgcn_global_load_lds((const unsigned*)((const char*)(gbase) + (voff)), (LAS unsigned*)(lds + (bufoff) + ldsw), 16, 0, 0); \
;         __builtin_amdgcn_global_load_lds((const unsigned*)((const char*)(gbase) + (q64) + (voff)), (LAS unsigned*)(lds + (bufoff) + ldsw + 8192), 16, 0, 0); } while (0)
; #define PG8_LDA(dst, b, h) do { _Pragma("unroll") for (int m = 0; m < 4; ++m) _Pragma("unroll") for (int k = 0; k < 2; ++k) dst[m][k] = *(const LAS bf16x8*)(lds + PG8_SA(b, h) + aoff + m * 2048 + k * 1024); } while (0)
; #define PG8_WAIT_V(n) asm volatile("s_waitcnt vmcnt(" #n ")" ::: "memory")
; #define PG8_WAIT_L(n) asm volatile("s_waitcnt lgkmcnt(" #n ")" ::: "memory")
; #define PG8_BAR __builtin_amdgcn_s_barrier()
; template <class Epi, class Sched>
; __device__ __forceinline__ void gemm_phase(LAS unsigned char* lds, const Gemm g, const Sched S, const Epi E, const int tid) {
;     ...
;             PG8_LDA(At, 1, 1); PG8_STAGE(PG8_SB(1, 0), b3, voffB); PG8_STAGE(PG8_SB(1, 1), b3 + hstepB, voffB); PG8_STAGE(PG8_SA(1, 0), a3, voffA);
;             PG8_WAIT_V(8); PG8_WAIT_L(0); PG8_BAR; PG8_MMA(1, 0, At, B0); PG8_MMA(1, 1, At, B1); PG8_BAR; PG8_SCHED;
;         }
	s_add_i32 s28, s41, s15
	v_lshl_add_u64 v[190:191], v[190:191], 0, s[0:1]
	s_mov_b32 m0, s28
	ds_read_b128 v[182:185], v153 offset:49152
	ds_read_b128 v[186:189], v153 offset:50176
	ds_read_b128 v[206:209], v153 offset:51200
	ds_read_b128 v[232:235], v153 offset:52224
	ds_read_b128 v[236:239], v153 offset:53248
	ds_read_b128 v[240:243], v153 offset:54272
	ds_read_b128 v[244:247], v153 offset:55296
	ds_read_b128 v[248:251], v153 offset:56320
	global_load_lds_dwordx4 v[190:191], off
	v_lshl_add_u64 v[190:191], v[210:211], 0, s[0:1]
	s_add_i32 m0, s28, 0x2000
	s_add_i32 s28, s48, s15
	global_load_lds_dwordx4 v[190:191], off
	v_lshl_add_u64 v[190:191], v[218:219], 0, s[0:1]
	s_mov_b32 m0, s28
	s_nop 0
	global_load_lds_dwordx4 v[190:191], off
	v_lshl_add_u64 v[190:191], v[220:221], 0, s[0:1]
	s_add_i32 m0, s28, 0x2000
	s_nop 0
	global_load_lds_dwordx4 v[190:191], off
	v_lshl_add_u64 v[190:191], v[192:193], 0, s[0:1]
	s_mov_b32 m0, s35
	s_nop 0
	global_load_lds_dwordx4 v[190:191], off
	v_lshl_add_u64 v[190:191], v[222:223], 0, s[0:1]
	s_mov_b32 m0, s52
	s_nop 0
	global_load_lds_dwordx4 v[190:191], off
	s_waitcnt vmcnt(8)
	s_waitcnt lgkmcnt(0)
	s_barrier
	s_setprio 1
	s_waitcnt lgkmcnt(0)
	v_mfma_f32_16x16x32_bf16 v[62:65], v[148:151], v[182:185], v[62:65]
	v_mfma_f32_16x16x32_bf16 v[58:61], v[158:161], v[182:185], v[58:61]
	v_mfma_f32_16x16x32_bf16 v[46:49], v[148:151], v[206:209], v[46:49]
	v_mfma_f32_16x16x32_bf16 v[42:45], v[158:161], v[206:209], v[42:45]
	v_mfma_f32_16x16x32_bf16 v[30:33], v[148:151], v[236:239], v[30:33]
	v_mfma_f32_16x16x32_bf16 v[26:29], v[158:161], v[236:239], v[26:29]
	v_mfma_f32_16x16x32_bf16 v[14:17], v[148:151], v[244:247], v[14:17]
	v_mfma_f32_16x16x32_bf16 v[10:13], v[158:161], v[244:247], v[10:13]
	v_mfma_f32_16x16x32_bf16 v[62:65], v[154:157], v[186:189], v[62:65]
	v_mfma_f32_16x16x32_bf16 v[58:61], v[162:165], v[186:189], v[58:61]
	v_mfma_f32_16x16x32_bf16 v[46:49], v[154:157], v[232:235], v[46:49]
	v_mfma_f32_16x16x32_bf16 v[42:45], v[162:165], v[232:235], v[42:45]
	v_mfma_f32_16x16x32_bf16 v[30:33], v[154:157], v[240:243], v[30:33]
	v_mfma_f32_16x16x32_bf16 v[26:29], v[162:165], v[240:243], v[26:29]
	v_mfma_f32_16x16x32_bf16 v[14:17], v[154:157], v[248:251], v[14:17]
	v_mfma_f32_16x16x32_bf16 v[10:13], v[162:165], v[248:251], v[10:13]
	s_setprio 0
	s_setprio 1
	v_mfma_f32_16x16x32_bf16 v[54:57], v[166:169], v[182:185], v[54:57]
	v_mfma_f32_16x16x32_bf16 v[50:53], v[174:177], v[182:185], v[50:53]
	v_mfma_f32_16x16x32_bf16 v[38:41], v[166:169], v[206:209], v[38:41]
	v_mfma_f32_16x16x32_bf16 v[34:37], v[174:177], v[206:209], v[34:37]
	v_mfma_f32_16x16x32_bf16 v[22:25], v[166:169], v[236:239], v[22:25]
	v_mfma_f32_16x16x32_bf16 v[18:21], v[174:177], v[236:239], v[18:21]
	v_mfma_f32_16x16x32_bf16 v[6:9], v[166:169], v[244:247], v[6:9]
	v_mfma_f32_16x16x32_bf16 v[2:5], v[174:177], v[244:247], v[2:5]
	v_mfma_f32_16x16x32_bf16 v[54:57], v[170:173], v[186:189], v[54:57]
	v_mfma_f32_16x16x32_bf16 v[50:53], v[178:181], v[186:189], v[50:53]
	v_mfma_f32_16x16x32_bf16 v[38:41], v[170:173], v[232:235], v[38:41]
	v_mfma_f32_16x16x32_bf16 v[34:37], v[178:181], v[232:235], v[34:37]
	v_mfma_f32_16x16x32_bf16 v[22:25], v[170:173], v[240:243], v[22:25]
	v_mfma_f32_16x16x32_bf16 v[18:21], v[178:181], v[240:243], v[18:21]
	v_mfma_f32_16x16x32_bf16 v[6:9], v[170:173], v[248:251], v[6:9]
	v_mfma_f32_16x16x32_bf16 v[2:5], v[178:181], v[248:251], v[2:5]
	s_setprio 0
	s_barrier
	s_add_u32 s38, s38, 0x100
	s_addc_u32 s39, s39, 0
	s_add_u32 s24, s24, 0x100
	s_addc_u32 s25, s25, 0
	s_cmp_ge_i32 s40, s54
	s_mov_b32 s28, s40
	s_cbranch_scc0 .LBB0_1100
	v_readlane_b32 s38, v254, 48
	v_readlane_b32 s39, v254, 49
